# P2: conv weights served from a per-workgroup LDS copy instead of 48 global loads per thread-item, plus next-item QKV L2 touch prefetch; on top of v43
# speedup vs baseline: 1.0482x; 1.0100x over previous
; DI void phase2(const P& p, char* smem, int bid, int nb) {
;   const int tid = threadIdx.x, lane = tid & 63, w = __builtin_amdgcn_readfirstlane(tid >> 6);
;   const u16* QKV = (const u16*)(p.ws + WS_BIG);
;   const float* BETA = (const float*)(p.ws + WS_BETA);
;   const float* G = (const float*)(p.ws + WS_G);
;   float* GL = (float*)(p.ws + WS_GL);
;   u16* NEGWU = (u16*)(p.out + O_KP);
;   u16* KDQG = (u16*)(p.out + O_VP);
;   u16* INTRA = (u16*)((char*)p.out + 67633152);
;   u16* Kb = (u16*)smem;
;   u16* Qb = Kb + 64 * 136;
;   float* Lf = (float*)(Qb + 64 * 136);
;   float* Tf = Lf + 64 * 65;
;   u16* Tb = (u16*)(Tf + 64 * 65);
;   u16* KBGt = Tb + 64 * 72;
;   u16* VBt = KBGt + 128 * 72;
;   float* Ys = (float*)(VBt + 128 * 72);
;   float* gc = Ys + 16 * 17;
;   float* bt = gc + 64;
;   for (int item = bid; item < 4096; item += nb) {
;     const int h = item & 7, n = (item >> 3) & 255, b = item >> 11;
;     const int tok0 = b * SEQ + n * 64;
;     const int sidx = (b * 8 + h) * 256 + n;
;     const int r = tid >> 3, seg = tid & 7;
;     __syncthreads();
;     if (tid < 64) {
;       float g = G[(tok0 + tid) * 8 + h];
;       for (int off = 1; off < 64; off <<= 1) { float o = __shfl_up(g, off); if (lane >= off) g += o; }
;       gc[tid] = g;
;       bt[tid] = BETA[(tok0 + tid) * 8 + h];
;       if (tid == 63) GL[(b * 8 + h) * 256 + n] = __expf(g);
.LBB0_121:
	s_load_dwordx4 s[52:55], s[0:1], 0x20
	s_load_dwordx2 s[4:5], s[0:1], 0xd8
	s_waitcnt lgkmcnt(0)
	s_cmp_lt_i32 s4, 3
	s_cselect_b64 s[28:29], -1, 0
	s_and_b64 s[2:3], s[28:29], s[2:3]
	s_andn2_b64 vcc, exec, s[2:3]
	s_cbranch_vccnz .LBB0_321
	v_writelane_b32 v251, s28, 23
	v_and_b32_e32 v59, 0x3ff, v0
	s_nop 0
	v_writelane_b32 v251, s29, 24
	v_readfirstlane_b32 s12, v59
	v_readlane_b32 s2, v251, 0
	s_cmpk_gt_i32 s2, 0xfff
	s_cbranch_scc1 .LBB0_320
	s_load_dwordx16 s[36:51], s[0:1], 0x98
	v_lshrrev_b32_e32 v63, 3, v59
	v_and_b32_e32 v3, 7, v59
	v_mul_u32_u24_e32 v4, 0x88, v63
	v_lshlrev_b32_e32 v4, 1, v4
	s_waitcnt lgkmcnt(0)
	s_add_u32 s16, s50, 0x5888000
	s_addc_u32 s17, s51, 0
	s_add_u32 s18, s50, 0x19b08000
	s_addc_u32 s19, s51, 0
	s_add_u32 s94, s50, 0x19c0a000
	v_lshlrev_b32_e32 v6, 5, v3
	s_addc_u32 s95, s51, 0
	v_add3_u32 v105, 0, v4, v6
	v_mul_u32_u24_e32 v6, 0x480, v3
	s_add_u32 s2, s50, 0x1c55c000
	v_lshlrev_b32_e32 v58, 4, v3
	v_lshrrev_b32_e32 v9, 6, v59
	v_lshl_or_b32 v4, v3, 10, v63
	v_and_or_b32 v3, v63, 7, v6
	v_writelane_b32 v251, s2, 25
	s_addc_u32 s2, s51, 0
	v_bitop3_b32 v7, v9, v59, 7 bitop3:0x78
	v_lshlrev_b32_e32 v3, 1, v3
	s_add_u32 s42, s48, 0x10100000
	v_lshl_or_b32 v3, v7, 4, v3
	s_addc_u32 s43, s49, 0
	s_add_i32 s13, 0, 0x12e00
	s_add_i32 s29, 0, 0x17600
	v_add_u32_e32 v7, 0x90, v3
	v_writelane_b32 v251, s2, 27
	v_cmp_eq_u32_e64 s[4:5], 63, v59
	v_add_u32_e32 v114, s13, v7
	v_add_u32_e32 v115, s29, v7
	v_add_u32_e32 v7, 0x120, v3
	v_and_b32_e32 v1, 63, v59
	v_writelane_b32 v251, s4, 29
	v_add_u32_e32 v116, s13, v7
	v_add_u32_e32 v117, s29, v7
	v_add_u32_e32 v7, 0x1b0, v3
	v_writelane_b32 v251, s5, 30
	v_cmp_eq_u32_e64 s[8:9], 0, v1
	v_add_u32_e32 v118, s13, v7
	v_add_u32_e32 v119, s29, v7
	v_add_u32_e32 v7, 0x240, v3
	v_and_b32_e32 v10, 15, v59
	v_writelane_b32 v251, s8, 45
	v_add_u32_e32 v120, s13, v7
	v_add_u32_e32 v121, s29, v7
	v_add_u32_e32 v7, 0x2d0, v3
	v_writelane_b32 v251, s9, 46
	v_cmp_gt_u32_e64 s[8:9], 2, v1
	v_add_u32_e32 v122, s13, v7
	v_add_u32_e32 v123, s29, v7
	v_add_u32_e32 v7, 0x360, v3
	v_cmp_eq_u32_e32 vcc, 0, v10
	v_lshrrev_b32_e32 v8, 2, v59
	s_movk_i32 s4, 0x100
	v_writelane_b32 v251, s8, 47
	v_add_u32_e32 v124, s13, v7
	v_add_u32_e32 v125, s29, v7
	v_add_u32_e32 v7, 0x3f0, v3
	v_cndmask_b32_e64 v163, 0, 1.0, vcc
	v_cmp_eq_u32_e32 vcc, 1, v10
	v_and_b32_e32 v62, 12, v8
	v_lshlrev_b32_e32 v8, 2, v10
	v_cmp_gt_u32_e64 s[6:7], s4, v59
	s_add_i32 s4, 0, 0x1be00
	v_writelane_b32 v251, s9, 48
	v_cmp_gt_u32_e64 s[8:9], 4, v1
	v_add_u32_e32 v126, s13, v7
	v_add_u32_e32 v127, s29, v7
	v_add_u32_e32 v7, 0x480, v3
	v_cndmask_b32_e64 v164, 0, 1.0, vcc
	v_cmp_eq_u32_e32 vcc, 2, v10
	v_bfe_u32 v12, v59, 4, 4
	v_add_u32_e32 v110, s4, v8
	s_movk_i32 s4, 0x44
	v_writelane_b32 v251, s8, 49
	v_add_u32_e32 v128, s13, v7
	v_add_u32_e32 v129, s29, v7
	v_add_u32_e32 v7, 0x510, v3
	v_cndmask_b32_e64 v166, 0, 1.0, vcc
	v_cmp_eq_u32_e32 vcc, 3, v10
	v_and_b32_e32 v6, 48, v59
	v_mad_u32_u24 v111, v12, s4, v110
	s_add_i32 s4, 0, 0x10a00
	v_writelane_b32 v251, s9, 50
	v_cmp_gt_u32_e64 s[8:9], 8, v1
	v_add_u32_e32 v130, s13, v7
	v_add_u32_e32 v131, s29, v7
	v_add_u32_e32 v7, 0x5a0, v3
	v_cndmask_b32_e64 v167, 0, 1.0, vcc
	v_cmp_eq_u32_e32 vcc, 4, v10
	v_lshrrev_b32_e32 v11, 4, v59
	v_add_u32_e32 v13, s4, v6
	v_writelane_b32 v251, s8, 51
	v_add_u32_e32 v132, s13, v7
	v_add_u32_e32 v133, s29, v7
	v_add_u32_e32 v7, 0x630, v3
	s_movk_i32 s33, 0x104
	v_cndmask_b32_e64 v168, 0, 1.0, vcc
	v_cmp_eq_u32_e32 vcc, 5, v10
	v_lshl_add_u32 v31, v1, 1, s4
	s_lshr_b32 s4, s12, 2
	s_add_i32 s11, 0, 0x1c240
	v_lshl_add_u32 v107, v6, 2, 0
	v_writelane_b32 v251, s9, 52
	v_cmp_gt_u32_e64 s[8:9], 16, v1
	v_add_u32_e32 v134, s13, v7
	v_add_u32_e32 v135, s29, v7
	v_add_u32_e32 v7, 0x6c0, v3
	v_cndmask_b32_e64 v169, 0, 1.0, vcc
	v_cmp_eq_u32_e32 vcc, 6, v10
	v_mad_u32_u24 v181, v11, s33, 0
	s_and_b32 s34, s4, 0x3ffffff0
	s_add_i32 s28, 0, 0x1c340
	v_add_u32_e32 v106, 0, v6
	v_add_u32_e32 v108, v107, v8
	v_add_u32_e32 v109, 0, v8
	v_writelane_b32 v251, s8, 53
	v_add_u32_e32 v136, s13, v7
	v_add_u32_e32 v137, s29, v7
	v_add_u32_e32 v7, 0x750, v3
	v_add_u32_e32 v159, s11, v8
	v_mul_u32_u24_e32 v165, 0x104, v6
	v_cndmask_b32_e64 v170, 0, 1.0, vcc
	v_cmp_eq_u32_e32 vcc, 7, v10
	v_or_b32_e32 v6, 15, v59
	v_add_u32_e32 v182, v181, v8
	v_or_b32_e32 v8, s34, v10
	v_mov_b32_e32 v61, 0
	v_writelane_b32 v251, s9, 54
	v_cmp_gt_u32_e64 s[8:9], 32, v1
	v_add_u32_e32 v138, s13, v7
	v_add_u32_e32 v139, s29, v7
	v_add_u32_e32 v7, 0x7e0, v3
	v_cndmask_b32_e64 v171, 0, 1.0, vcc
	v_cmp_eq_u32_e32 vcc, 8, v10
	v_mul_u32_u24_e32 v180, 0x104, v6
	v_lshlrev_b32_e32 v6, 6, v59
	v_lshlrev_b32_e32 v60, 1, v62
	s_cmpk_lt_u32 s12, 0x100
	v_subrev_u32_e32 v35, 64, v8
	v_writelane_b32 v251, s8, 55
	v_add_u32_e32 v140, s13, v7
	v_add_u32_e32 v141, s29, v7
	s_movk_i32 s14, 0x110
	v_cndmask_b32_e64 v172, 0, 1.0, vcc
	v_cmp_eq_u32_e32 vcc, 9, v10
	v_and_b32_e32 v34, 0x3c0, v6
	v_lshl_add_u64 v[6:7], s[48:49], 0, v[60:61]
	s_cselect_b64 s[4:5], -1, 0
	s_cmpk_gt_u32 s12, 0xff
	v_lshlrev_b32_e32 v60, 6, v35
	v_writelane_b32 v251, s9, 56
	v_cndmask_b32_e64 v173, 0, 1.0, vcc
	v_cmp_eq_u32_e32 vcc, 10, v10
	s_cselect_b64 s[8:9], -1, 0
	v_mul_lo_u32 v183, v8, s14
	v_lshl_add_u64 v[6:7], v[60:61], 1, v[6:7]
	s_mov_b64 s[14:15], 0x4080000
	v_add_u32_e32 v112, s13, v3
	v_add_u32_e32 v113, s29, v3
	v_add_u32_e32 v3, 0x870, v3
	v_cndmask_b32_e64 v174, 0, 1.0, vcc
	v_cmp_eq_u32_e32 vcc, 11, v10
	v_lshl_add_u64 v[66:67], v[6:7], 0, s[14:15]
	s_and_b64 s[14:15], s[8:9], exec
	v_add_u32_e32 v142, s13, v3
	v_add_u32_e32 v143, s29, v3
	v_cndmask_b32_e64 v175, 0, 1.0, vcc
; DI void phase2(const P& p, char* smem, int bid, int nb) {
;   const int tid = threadIdx.x, lane = tid & 63, w = __builtin_amdgcn_readfirstlane(tid >> 6);
;   const u16* QKV = (const u16*)(p.ws + WS_BIG);
;   const float* BETA = (const float*)(p.ws + WS_BETA);
;   const float* G = (const float*)(p.ws + WS_G);
;   float* GL = (float*)(p.ws + WS_GL);
;   u16* NEGWU = (u16*)(p.out + O_KP);
;   u16* KDQG = (u16*)(p.out + O_VP);
;   u16* INTRA = (u16*)((char*)p.out + 67633152);
;   u16* Kb = (u16*)smem;
;   u16* Qb = Kb + 64 * 136;
;   float* Lf = (float*)(Qb + 64 * 136);
;   float* Tf = Lf + 64 * 65;
;   u16* Tb = (u16*)(Tf + 64 * 65);
;   u16* KBGt = Tb + 64 * 72;
;   u16* VBt = KBGt + 128 * 72;
;   float* Ys = (float*)(VBt + 128 * 72);
;   float* gc = Ys + 16 * 17;
;   float* bt = gc + 64;
;   for (int item = bid; item < 4096; item += nb) {
;     const int h = item & 7, n = (item >> 3) & 255, b = item >> 11;
;     const int tok0 = b * SEQ + n * 64;
;     const int sidx = (b * 8 + h) * 256 + n;
;     const int r = tid >> 3, seg = tid & 7;
;     __syncthreads();
;     if (tid < 64) {
;       float g = G[(tok0 + tid) * 8 + h];
;       for (int off = 1; off < 64; off <<= 1) { float o = __shfl_up(g, off); if (lane >= off) g += o; }
;       gc[tid] = g;
;       bt[tid] = BETA[(tok0 + tid) * 8 + h];
;       if (tid == 63) GL[(b * 8 + h) * 256 + n] = __expf(g);
	v_cmp_eq_u32_e32 vcc, 12, v10
	s_cselect_b32 s29, s29, s13
	s_cselect_b32 s13, 0x4000, 0
	v_mbcnt_lo_u32_b32 v7, -1, 0
	v_cndmask_b32_e64 v176, 0, 1.0, vcc
	v_cmp_eq_u32_e32 vcc, 13, v10
	s_add_u32 s13, s48, s13
	v_mbcnt_hi_u32_b32 v7, -1, v7
	v_cndmask_b32_e64 v177, 0, 1.0, vcc
	v_cmp_eq_u32_e32 vcc, 14, v10
	s_addc_u32 s14, s49, 0
	v_and_b32_e32 v37, 64, v7
	v_cndmask_b32_e64 v178, 0, 1.0, vcc
	v_cmp_eq_u32_e32 vcc, 15, v10
	s_add_u32 s44, s13, 0x8100000
	v_xor_b32_e32 v8, 1, v7
	v_add_u32_e32 v38, 64, v37
	v_cndmask_b32_e64 v179, 0, 1.0, vcc
	v_or_b32_e32 v6, s34, v62
	s_addc_u32 s45, s14, 0
	s_lshr_b32 s34, s12, 5
	v_cmp_lt_i32_e32 vcc, v8, v38
	v_cmp_le_i32_e64 s[12:13], v62, v35
	v_lshlrev_b32_e32 v12, 7, v59
	v_cndmask_b32_e32 v8, v7, v8, vcc
	v_writelane_b32 v251, s12, 57
	v_lshlrev_b32_e32 v185, 2, v8
	v_xor_b32_e32 v8, 2, v7
	v_writelane_b32 v251, s13, 58
	v_cmp_lt_i32_e64 s[12:13], v62, v35
	v_and_b32_e32 v64, 0x780, v12
	v_or_b32_e32 v12, 2, v62
	v_cmp_lt_i32_e32 vcc, v8, v38
	v_writelane_b32 v251, s12, 59
	v_or_b32_e32 v14, 3, v62
	v_cndmask_b32_e32 v8, v7, v8, vcc
	v_writelane_b32 v251, s13, 60
	v_cmp_le_i32_e64 s[12:13], v12, v35
	v_lshlrev_b32_e32 v186, 2, v8
	v_xor_b32_e32 v8, 4, v7
	v_writelane_b32 v251, s12, 61
	v_cmp_lt_i32_e32 vcc, v8, v38
	v_or_b32_e32 v15, 16, v62
	v_writelane_b32 v251, s13, 62
	v_cmp_le_i32_e64 s[12:13], v14, v35
	v_cndmask_b32_e32 v8, v7, v8, vcc
	v_lshlrev_b32_e32 v188, 2, v8
	v_writelane_b32 v251, s12, 63
	v_lshlrev_b32_e32 v8, 2, v6
	v_or_b32_e32 v16, 17, v62
	v_writelane_b32 v252, s13, 0
	v_cmp_le_i32_e64 s[12:13], v15, v35
	v_add_u32_e32 v189, s28, v8
	v_add_u32_e32 v190, s11, v8
	v_writelane_b32 v252, s12, 1
	v_or_b32_e32 v8, 4, v8
	v_add_u32_e32 v191, s28, v8
	v_writelane_b32 v252, s13, 2
	v_cmp_le_i32_e64 s[12:13], v16, v35
	v_add_u32_e32 v192, s11, v8
	v_or_b32_e32 v8, 2, v6
	v_lshl_add_u32 v145, v12, 2, s11
	v_or_b32_e32 v17, 18, v62
	v_writelane_b32 v252, s12, 3
	v_lshlrev_b32_e32 v12, 2, v8
	v_add_u32_e32 v193, s28, v12
	v_writelane_b32 v252, s13, 4
	v_cmp_le_i32_e64 s[12:13], v17, v35
	v_add_u32_e32 v194, s11, v12
	v_or_b32_e32 v12, 3, v6
	v_lshlrev_b32_e32 v5, 2, v59
	v_lshlrev_b32_e32 v2, 2, v63
	v_lshl_add_u32 v147, v15, 2, s11
	v_or_b32_e32 v18, 19, v62
	v_or_b32_e32 v19, 32, v62
	v_or_b32_e32 v20, 33, v62
	v_or_b32_e32 v21, 34, v62
	v_or_b32_e32 v22, 35, v62
	v_or_b32_e32 v23, 48, v62
	v_or_b32_e32 v24, 49, v62
	v_or_b32_e32 v25, 50, v62
	v_or_b32_e32 v26, 51, v62
	v_or_b32_e32 v27, 16, v10
	v_or_b32_e32 v29, 32, v10
	v_or_b32_e32 v30, 48, v10
	s_and_b32 s35, s34, 6
	v_writelane_b32 v252, s12, 5
	v_lshlrev_b32_e32 v15, 2, v12
	v_add_u32_e32 v65, s11, v5
	v_add_u32_e32 v103, s11, v2
	v_lshl_add_u32 v144, v62, 2, s11
	v_lshl_add_u32 v146, v14, 2, s11
	v_lshl_add_u32 v148, v16, 2, s11
	v_lshl_add_u32 v149, v17, 2, s11
	v_lshl_add_u32 v150, v18, 2, s11
	v_lshl_add_u32 v151, v19, 2, s11
	v_lshl_add_u32 v152, v20, 2, s11
	v_lshl_add_u32 v153, v21, 2, s11
	v_lshl_add_u32 v154, v22, 2, s11
	v_lshl_add_u32 v155, v23, 2, s11
	v_lshl_add_u32 v156, v24, 2, s11
	v_lshl_add_u32 v157, v25, 2, s11
	v_lshl_add_u32 v158, v26, 2, s11
	v_lshl_add_u32 v160, v27, 2, s11
	v_lshl_add_u32 v161, v29, 2, s11
	v_lshl_add_u32 v162, v30, 2, s11
	v_lshl_add_u32 v184, v35, 2, s11
	v_writelane_b32 v252, s13, 6
	v_cmp_le_i32_e64 s[12:13], v18, v35
	v_add_u32_e32 v197, s11, v15
	s_lshl_b32 s11, s35, 4
	s_movk_i32 s10, 0x90
	v_lshl_add_u32 v11, v1, 2, 0
	v_bfe_u32 v1, v59, 4, 2
	v_writelane_b32 v252, s12, 7
	v_cmp_lt_u32_e64 s[14:15], v10, v6
	v_mul_lo_u32 v14, v6, s33
	v_cmp_le_u32_e64 s[56:57], v10, v6
	v_cmp_lt_u32_e64 s[60:61], v10, v12
	v_cmp_lt_u32_e64 s[62:63], v27, v6
	v_cmp_le_u32_e64 s[64:65], v27, v6
	v_cmp_lt_u32_e64 s[68:69], v27, v12
	v_cmp_lt_u32_e64 s[70:71], v29, v6
	v_cmp_le_u32_e64 s[72:73], v29, v6
	v_cmp_lt_u32_e64 s[76:77], v29, v12
	v_cmp_lt_u32_e64 s[78:79], v30, v6
	v_cmp_le_u32_e64 s[80:81], v30, v6
	v_cmp_lt_u32_e64 s[84:85], v30, v12
	v_or_b32_e32 v6, s11, v10
	v_mov_b32_e32 v12, s29
	v_or_b32_e32 v33, 4, v1
	v_writelane_b32 v252, s13, 8
	v_cmp_le_i32_e64 s[12:13], v19, v35
	v_add_u32_e32 v196, s28, v15
	v_mad_u32_u24 v15, v6, s10, v12
	v_bitop3_b32 v6, s34, v1, 6 bitop3:0x6c
	v_bitop3_b32 v1, s35, v1, 1 bitop3:0x36
	v_writelane_b32 v252, s12, 9
	v_lshlrev_b32_e32 v19, 4, v1
	v_bitop3_b32 v1, s35, v33, 1 bitop3:0x36
	v_writelane_b32 v252, s13, 10
	v_cmp_le_i32_e64 s[12:13], v20, v35
	v_lshlrev_b32_e32 v20, 4, v1
	v_add_u32_e32 v1, -1, v7
	v_cmp_lt_i32_e32 vcc, v1, v37
	v_writelane_b32 v252, s12, 11
	v_lshlrev_b32_e32 v16, 4, v6
	v_cndmask_b32_e32 v1, v1, v7, vcc
	v_lshlrev_b32_e32 v198, 2, v1
	v_add_u32_e32 v1, -2, v7
; DI void phase2(const P& p, char* smem, int bid, int nb) {
;   const int tid = threadIdx.x, lane = tid & 63, w = __builtin_amdgcn_readfirstlane(tid >> 6);
;   const u16* QKV = (const u16*)(p.ws + WS_BIG);
;   const float* BETA = (const float*)(p.ws + WS_BETA);
;   const float* G = (const float*)(p.ws + WS_G);
;   float* GL = (float*)(p.ws + WS_GL);
;   u16* NEGWU = (u16*)(p.out + O_KP);
;   u16* KDQG = (u16*)(p.out + O_VP);
;   u16* INTRA = (u16*)((char*)p.out + 67633152);
;   u16* Kb = (u16*)smem;
;   u16* Qb = Kb + 64 * 136;
;   float* Lf = (float*)(Qb + 64 * 136);
;   float* Tf = Lf + 64 * 65;
;   u16* Tb = (u16*)(Tf + 64 * 65);
;   u16* KBGt = Tb + 64 * 72;
;   u16* VBt = KBGt + 128 * 72;
;   float* Ys = (float*)(VBt + 128 * 72);
;   float* gc = Ys + 16 * 17;
;   float* bt = gc + 64;
;   for (int item = bid; item < 4096; item += nb) {
;     ...
;           const float4* cw = (const float4*)(p.conv_w + j * 3072 + col);
;           float4 c0 = cw[0], c1 = cw[1], c2 = cw[2], c3 = cw[3];
	v_cmp_lt_i32_e32 vcc, v1, v37
	v_writelane_b32 v252, s13, 12
	v_cmp_le_i32_e64 s[12:13], v21, v35
	v_cndmask_b32_e32 v1, v1, v7, vcc
	v_lshlrev_b32_e32 v199, 2, v1
	v_add_u32_e32 v1, -4, v7
	v_cmp_lt_i32_e32 vcc, v1, v37
	v_writelane_b32 v252, s12, 13
	v_bitop3_b32 v6, s34, v33, 6 bitop3:0x6c
	v_cndmask_b32_e32 v1, v1, v7, vcc
	v_lshlrev_b32_e32 v200, 2, v1
	v_add_u32_e32 v1, -8, v7
	v_cmp_lt_i32_e32 vcc, v1, v37
	v_writelane_b32 v252, s13, 14
	v_cmp_le_i32_e64 s[12:13], v22, v35
	v_cndmask_b32_e32 v1, v1, v7, vcc
	v_lshlrev_b32_e32 v202, 2, v1
	v_add_u32_e32 v1, -16, v7
	v_cmp_lt_i32_e32 vcc, v1, v37
	v_lshlrev_b32_e32 v17, 4, v6
	v_or_b32_e32 v6, s11, v62
	s_or_b32 s11, s35, 1
	v_cndmask_b32_e32 v1, v1, v7, vcc
	v_add_u32_e32 v69, s28, v5
	v_add_u32_e32 v104, s28, v2
	v_writelane_b32 v252, s12, 15
	s_lshl_b32 s28, s11, 4
	v_lshlrev_b32_e32 v203, 2, v1
	v_subrev_u32_e32 v1, 32, v7
	v_mul_u32_u24_e32 v3, 0x110, v10
	v_mul_u32_u24_e32 v32, 0x90, v10
	v_writelane_b32 v252, s13, 16
	v_cmp_le_i32_e64 s[12:13], v23, v35
	v_cmp_lt_u32_e64 s[58:59], v10, v8
	v_or_b32_e32 v10, s28, v10
	v_cmp_lt_i32_e32 vcc, v1, v37
	v_mul_u32_u24_e32 v28, 0x110, v27
	v_writelane_b32 v252, s12, 17
	v_cmp_lt_u32_e64 s[66:67], v27, v8
	v_mad_u32_u24 v18, v10, s10, v12
	v_cndmask_b32_e32 v1, v1, v7, vcc
	v_or_b32_e32 v27, 0xc00, v59
	s_movk_i32 s10, 0xe00
	v_writelane_b32 v252, s13, 18
	v_cmp_le_i32_e64 s[12:13], v24, v35
	v_cmp_le_i32_e64 s[50:51], v25, v35
	v_cmp_lt_u32_e64 s[74:75], v29, v8
	v_lshlrev_b32_e32 v204, 2, v1
	v_sub_u32_e32 v1, 0x103f, v59
	v_add_u32_e32 v21, 0x200, v59
	v_add_u32_e32 v23, 0x600, v59
	v_add_u32_e32 v25, 0xa00, v59
	v_lshrrev_b32_e32 v29, 6, v27
	v_cmp_gt_u32_e64 s[86:87], s10, v27
	v_add_u32_e32 v27, 0xe00, v59
	v_writelane_b32 v252, s12, 19
	v_lshrrev_b32_e32 v68, 9, v1
	v_lshrrev_b32_e32 v21, 6, v21
	v_lshrrev_b32_e32 v23, 6, v23
	v_lshrrev_b32_e32 v25, 6, v25
	v_lshrrev_b32_e32 v27, 6, v27
	s_mov_b32 s96, 0
	v_lshlrev_b32_e32 v2, 7, v63
	v_add_u32_e32 v36, 0xffffbc00, v183
	v_writelane_b32 v252, s13, 20
	v_cmp_le_i32_e64 s[12:13], v26, v35
	v_cmp_lt_u32_e64 s[82:83], v30, v8
	v_lshl_or_b32 v8, s35, 10, v34
	v_or_b32_e32 v10, s28, v62
	v_lshl_or_b32 v12, s11, 10, v34
	v_add_u32_e32 v1, 2, v68
	v_mul_u32_u24_e32 v7, 0x104, v9
	v_mul_u32_u24_e32 v9, 0x90, v9
	v_mul_u32_u24_e32 v22, 0x104, v21
	v_mul_u32_u24_e32 v21, 0x90, v21
	v_mul_u32_u24_e32 v24, 0x104, v23
	v_mul_u32_u24_e32 v23, 0x90, v23
	v_mul_u32_u24_e32 v26, 0x104, v25
	v_mul_u32_u24_e32 v25, 0x90, v25
	v_mul_u32_u24_e32 v30, 0x104, v29
	v_mul_u32_u24_e32 v29, 0x90, v29
	v_mul_u32_u24_e32 v33, 0x104, v27
	v_mul_u32_u24_e32 v27, 0x90, v27
	v_add_u32_e32 v5, 0, v5
	v_cmp_gt_u32_e64 s[2:3], 64, v59
	s_mov_b32 s97, 1
	v_add_u32_e32 v102, -3, v63
	v_and_b32_e32 v205, 30, v1
	v_mov_b32_e32 v1, v68
	v_add_u32_e32 v206, 0xc900, v5
	s_movk_i32 s46, 0x1800
	s_mov_b64 s[28:29], 0x3000
	s_mov_b64 s[10:11], 0x6000
	s_mov_b64 s[34:35], 0x9000
	s_mov_b32 s47, 0x9000
	s_mov_b32 s48, 0x800000
	s_add_i32 s49, 0, 0x1c33c
	v_lshlrev_b32_e32 v70, 1, v2
	v_lshlrev_b32_e32 v72, 1, v58
	v_lshlrev_b32_e32 v207, 1, v4
	v_add_u32_e32 v208, v106, v36
	v_add_u32_e32 v209, v106, v28
	v_add_u32_e32 v213, v11, v7
	v_add_u32_e32 v214, v31, v9
	v_add_u32_e32 v215, v11, v22
	v_add_u32_e32 v216, v31, v21
	v_add_u32_e32 v217, v11, v24
	v_add_u32_e32 v218, v31, v23
	v_add_u32_e32 v219, v11, v26
	v_add_u32_e32 v220, v31, v25
	v_add_u32_e32 v221, v11, v30
	v_add_u32_e32 v222, v31, v29
	v_add_u32_e32 v223, v11, v33
	v_add_u32_e32 v224, v31, v27
	v_add_u32_e32 v225, v15, v16
	v_add_u32_e32 v226, v15, v17
	v_lshlrev_b32_e32 v74, 1, v6
	v_lshlrev_b32_e32 v76, 1, v8
	v_add_u32_e32 v227, v18, v19
	v_add_u32_e32 v228, v18, v20
	v_lshlrev_b32_e32 v78, 1, v10
	v_lshlrev_b32_e32 v80, 1, v12
	v_add_u32_e32 v229, v106, v3
	v_add_u32_e32 v230, v109, v14
	v_add_u32_e32 v231, v13, v32
	v_readlane_b32 s100, v251, 0
	s_and_b32 s100, s100, 7
	s_lshl_b32 s100, s100, 9
	s_add_u32 s100, s30, s100
	s_addc_u32 s101, s31, 0
	v_and_b32_e32 v244, 0x3ff, v0
	v_cmp_gt_u32_e32 vcc, 0x180, v244
	v_lshrrev_b32_e32 v245, 5, v244
	v_and_b32_e32 v246, 31, v244
	v_lshlrev_b32_e32 v248, 12, v245
	v_lshl_add_u32 v248, v246, 4, v248
	v_mov_b32_e32 v249, 0
	v_lshl_add_u64 v[248:249], s[100:101], 0, v[248:249]
	v_lshlrev_b32_e32 v245, 9, v245
	v_lshl_add_u32 v245, v246, 4, v245
	v_add_u32_e32 v245, 0x1e000, v245
	s_and_saveexec_b64 vcc, vcc
	s_cbranch_execz .Lp2_fill_done
	global_load_dwordx4 v[246:249], v[248:249], off
	s_waitcnt vmcnt(0)
	ds_write_b128 v245, v[246:249]
	s_waitcnt lgkmcnt(0)
.Lp2_fill_done:
	s_mov_b64 exec, vcc
	v_readlane_b32 s33, v251, 0
	s_branch .LBB0_125

; DI float bflo(u32 w) { return __uint_as_float(w << 16); }
; DI float bfhi(u32 w) { return __uint_as_float(w & 0xffff0000u); }
; DI void phase2(const P& p, char* smem, int bid, int nb) {
;     ...
;   for (int item = bid; item < 4096; item += nb) {
;     const int h = item & 7, n = (item >> 3) & 255, b = item >> 11;
;     const int tok0 = b * SEQ + n * 64;
;     const int sidx = (b * 8 + h) * 256 + n;
;     const int r = tid >> 3, seg = tid & 7;
;     __syncthreads();
;     if (tid < 64) {
;       float g = G[(tok0 + tid) * 8 + h];
;       for (int off = 1; off < 64; off <<= 1) { float o = __shfl_up(g, off); if (lane >= off) g += o; }
;       gc[tid] = g;
;       bt[tid] = BETA[(tok0 + tid) * 8 + h];
;       if (tid == 63) GL[(b * 8 + h) * 256 + n] = __expf(g);
;     }
;     float qv[16], kv[16], vv[16];
; #pragma unroll
;     for (int mat = 0; mat < 3; mat++) {
;       float val[16];
; #pragma unroll
;       for (int c = 0; c < 16; c++) val[c] = 0.f;
;       const int col = mat * 1024 + h * 128 + seg * 16;
; #pragma unroll
;       for (int j = 0; j < 4; j++) {
;         int tl = n * 64 + r - 3 + j;
;         if (tl >= 0) {
;           const u16* src = QKV + (size_t)(tok0 + r - 3 + j) * 3072 + col;
;           u32x4 r0 = *(const u32x4*)src, r1 = *(const u32x4*)(src + 8);
;           const float4* cw = (const float4*)(p.conv_w + j * 3072 + col);
;           float4 c0 = cw[0], c1 = cw[1], c2 = cw[2], c3 = cw[3];
;           val[0] += c0.x * bflo(r0[0]); val[1] += c0.y * bfhi(r0[0]); val[2] += c0.z * bflo(r0[1]); val[3] += c0.w * bfhi(r0[1]);
;           val[4] += c1.x * bflo(r0[2]); val[5] += c1.y * bfhi(r0[2]); val[6] += c1.z * bflo(r0[3]); val[7] += c1.w * bfhi(r0[3]);
;           val[8] += c2.x * bflo(r1[0]); val[9] += c2.y * bfhi(r1[0]); val[10] += c2.z * bflo(r1[1]); val[11] += c2.w * bfhi(r1[1]);
;           val[12] += c3.x * bflo(r1[2]); val[13] += c3.y * bfhi(r1[2]); val[14] += c3.z * bflo(r1[3]); val[15] += c3.w * bfhi(r1[3]);
;         }
.LBB0_125:
	s_bfe_u32 s36, s33, 0x80003
	s_lshl_b32 s37, s33, 3
	s_and_b32 s41, s33, 7
	s_and_b32 s37, s37, 0xffffc000
	s_lshl_b32 s88, s36, 6
	s_or_b32 s40, s88, s37
	s_and_b32 s37, s33, 0xfffff800
	s_lshl_b32 s38, s41, 8
	s_or_b32 s37, s38, s37
	s_or_b32 s36, s37, s36
	s_barrier
	s_and_saveexec_b64 s[38:39], s[2:3]
	s_cbranch_execz .LBB0_128
	v_or_b32_e32 v2, s40, v59
	v_lshl_or_b32 v2, v2, 3, s41
	v_ashrrev_i32_e32 v3, 31, v2
	v_lshlrev_b64 v[2:3], 2, v[2:3]
	v_lshl_add_u64 v[4:5], s[94:95], 0, v[2:3]
	global_load_dword v4, v[4:5], off
	v_lshl_add_u64 v[2:3], s[18:19], 0, v[2:3]
	global_load_dword v3, v[2:3], off
	v_readlane_b32 s90, v251, 45
	v_readlane_b32 s91, v251, 46
	s_waitcnt vmcnt(0)
	s_waitcnt lgkmcnt(0)
	ds_bpermute_b32 v2, v198, v4
	s_waitcnt lgkmcnt(0)
	v_add_f32_e32 v2, v4, v2
	v_cndmask_b32_e64 v2, v2, v4, s[90:91]
	ds_bpermute_b32 v4, v199, v2
	v_readlane_b32 s90, v251, 47
	v_readlane_b32 s91, v251, 48
	s_waitcnt lgkmcnt(0)
	v_add_f32_e32 v4, v2, v4
	v_cndmask_b32_e64 v2, v4, v2, s[90:91]
	ds_bpermute_b32 v4, v200, v2
	v_readlane_b32 s90, v251, 49
	v_readlane_b32 s91, v251, 50
	s_waitcnt lgkmcnt(0)
	v_add_f32_e32 v4, v2, v4
	v_cndmask_b32_e64 v2, v4, v2, s[90:91]
	ds_bpermute_b32 v4, v202, v2
	v_readlane_b32 s90, v251, 51
	v_readlane_b32 s91, v251, 52
	s_waitcnt lgkmcnt(0)
	v_add_f32_e32 v4, v2, v4
	v_cndmask_b32_e64 v2, v4, v2, s[90:91]
	ds_bpermute_b32 v4, v203, v2
	v_readlane_b32 s90, v251, 53
	v_readlane_b32 s91, v251, 54
	s_waitcnt lgkmcnt(0)
	v_add_f32_e32 v4, v2, v4
	v_cndmask_b32_e64 v4, v4, v2, s[90:91]
	ds_bpermute_b32 v2, v204, v4
	v_readlane_b32 s90, v251, 55
	v_readlane_b32 s91, v251, 56
	s_waitcnt lgkmcnt(0)
	v_add_f32_e32 v2, v4, v2
	v_cndmask_b32_e64 v4, v2, v4, s[90:91]
	v_readlane_b32 s90, v251, 29
	v_readlane_b32 s91, v251, 30
	ds_write_b32 v65, v4
	s_waitcnt vmcnt(0)
	s_waitcnt lgkmcnt(0)
	ds_write_b32 v69, v3
	s_and_b64 exec, exec, s[90:91]
	s_cbranch_execz .LBB0_128
	v_mul_f32_e32 v2, 0x3fb8aa3b, v2
	v_exp_f32_e32 v2, v2
	s_ashr_i32 s37, s36, 31
	s_lshl_b64 s[90:91], s[36:37], 2
	v_readlane_b32 s37, v251, 25
	s_add_u32 s90, s37, s90
	v_readlane_b32 s37, v251, 27
	s_addc_u32 s91, s37, s91
	global_store_dword v61, v2, s[90:91]
.LBB0_128:
	s_or_b64 exec, exec, s[38:39]
	v_lshl_or_b32 v77, s41, 7, v58
	v_lshlrev_b32_e32 v60, 1, v77
	v_add_u32_e32 v8, s88, v63
	v_lshl_add_u64 v[2:3], s[16:17], 0, v[60:61]
	v_lshlrev_b32_e32 v60, 2, v77
	v_mov_b32_e32 v4, 0
	v_add_u32_e32 v71, s40, v102
	v_lshl_add_u64 v[6:7], s[30:31], 0, v[60:61]
	v_cmp_lt_u32_e64 s[88:89], 2, v8
	v_mov_b32_e32 v5, 0
	v_mov_b32_e32 v22, 0
	v_mov_b32_e32 v23, 0
	v_mov_b32_e32 v24, 0
	v_mov_b32_e32 v25, v4
	v_mov_b32_e32 v26, v4
	v_mov_b32_e32 v27, v4
	v_mov_b32_e32 v28, v4
	v_mov_b32_e32 v29, v4
	v_mov_b32_e32 v30, v4
	v_mov_b32_e32 v31, v4
	v_mov_b32_e32 v32, v4
	v_mov_b32_e32 v33, v4
	v_mov_b32_e32 v34, v4
	v_mov_b32_e32 v35, v4
	v_mov_b32_e32 v36, 0
	v_mov_b32_e32 v37, 0
	s_and_saveexec_b64 s[38:39], s[88:89]
	s_cbranch_execz .LBB0_130
	v_mad_i64_i32 v[4:5], s[90:91], v71, s46, v[2:3]
	global_load_dwordx4 v[10:13], v[4:5], off offset:16
	global_load_dwordx4 v[14:17], v[4:5], off
	v_subrev_u32_e32 v248, s100, v6
	v_lshrrev_b32_e32 v249, 12, v248
	v_and_b32_e32 v248, 0xfff, v248
	v_lshl_add_u32 v248, v249, 9, v248
	v_add_u32_e32 v248, 0x1e000, v248
	ds_read_b128 v[18:21], v248 offset:48
	v_subrev_u32_e32 v248, s100, v6
	v_lshrrev_b32_e32 v249, 12, v248
	v_and_b32_e32 v248, 0xfff, v248
	v_lshl_add_u32 v248, v249, 9, v248
	v_add_u32_e32 v248, 0x1e000, v248
	ds_read_b128 v[30:33], v248 offset:32
	v_subrev_u32_e32 v248, s100, v6
	v_lshrrev_b32_e32 v249, 12, v248
	v_and_b32_e32 v248, 0xfff, v248
	v_lshl_add_u32 v248, v249, 9, v248
	v_add_u32_e32 v248, 0x1e000, v248
	ds_read_b128 v[26:29], v248 offset:16
	v_subrev_u32_e32 v248, s100, v6
	v_lshrrev_b32_e32 v249, 12, v248
	v_and_b32_e32 v248, 0xfff, v248
	v_lshl_add_u32 v248, v249, 9, v248
	v_add_u32_e32 v248, 0x1e000, v248
	ds_read_b128 v[22:25], v248
	s_waitcnt vmcnt(0)
	s_waitcnt lgkmcnt(0)
	v_lshlrev_b32_e32 v4, 16, v14
	v_and_b32_e32 v5, 0xffff0000, v14
	s_waitcnt vmcnt(0)
	s_waitcnt lgkmcnt(0)
	v_pk_fma_f32 v[22:23], v[22:23], v[4:5], 0 op_sel_hi:[1,1,0]
	v_lshlrev_b32_e32 v4, 16, v15
	v_and_b32_e32 v5, 0xffff0000, v15
	v_pk_fma_f32 v[24:25], v[24:25], v[4:5], 0 op_sel_hi:[1,1,0]
	v_lshlrev_b32_e32 v4, 16, v16
	v_and_b32_e32 v5, 0xffff0000, v16
	v_pk_fma_f32 v[26:27], v[26:27], v[4:5], 0 op_sel_hi:[1,1,0]
	v_lshlrev_b32_e32 v4, 16, v17
	v_and_b32_e32 v5, 0xffff0000, v17
	v_pk_fma_f32 v[28:29], v[28:29], v[4:5], 0 op_sel_hi:[1,1,0]
	v_lshlrev_b32_e32 v4, 16, v10
	v_and_b32_e32 v5, 0xffff0000, v10
	v_pk_fma_f32 v[30:31], v[30:31], v[4:5], 0 op_sel_hi:[1,1,0]
	v_lshlrev_b32_e32 v4, 16, v11
	v_and_b32_e32 v5, 0xffff0000, v11
	v_pk_fma_f32 v[32:33], v[32:33], v[4:5], 0 op_sel_hi:[1,1,0]
	v_lshlrev_b32_e32 v4, 16, v12
	v_and_b32_e32 v5, 0xffff0000, v12
	v_pk_fma_f32 v[34:35], v[18:19], v[4:5], 0 op_sel_hi:[1,1,0]
	v_lshlrev_b32_e32 v4, 16, v13
	v_and_b32_e32 v5, 0xffff0000, v13
	v_pk_fma_f32 v[4:5], v[20:21], v[4:5], 0 op_sel_hi:[1,1,0]
	s_nop 0
	v_mov_b32_e32 v36, v4
	v_mov_b32_e32 v37, v5
; DI float bflo(u32 w) { return __uint_as_float(w << 16); }
; DI float bfhi(u32 w) { return __uint_as_float(w & 0xffff0000u); }
; DI void phase2(const P& p, char* smem, int bid, int nb) {
;     ...
; #pragma unroll
;       for (int j = 0; j < 4; j++) {
;         int tl = n * 64 + r - 3 + j;
;         if (tl >= 0) {
;           const u16* src = QKV + (size_t)(tok0 + r - 3 + j) * 3072 + col;
;           u32x4 r0 = *(const u32x4*)src, r1 = *(const u32x4*)(src + 8);
;           const float4* cw = (const float4*)(p.conv_w + j * 3072 + col);
;           float4 c0 = cw[0], c1 = cw[1], c2 = cw[2], c3 = cw[3];
;           val[0] += c0.x * bflo(r0[0]); val[1] += c0.y * bfhi(r0[0]); val[2] += c0.z * bflo(r0[1]); val[3] += c0.w * bfhi(r0[1]);
;           val[4] += c1.x * bflo(r0[2]); val[5] += c1.y * bfhi(r0[2]); val[6] += c1.z * bflo(r0[3]); val[7] += c1.w * bfhi(r0[3]);
;           val[8] += c2.x * bflo(r1[0]); val[9] += c2.y * bfhi(r1[0]); val[10] += c2.z * bflo(r1[1]); val[11] += c2.w * bfhi(r1[1]);
;           val[12] += c3.x * bflo(r1[2]); val[13] += c3.y * bfhi(r1[2]); val[14] += c3.z * bflo(r1[3]); val[15] += c3.w * bfhi(r1[3]);
;         }
.LBB0_130:
	s_or_b64 exec, exec, s[38:39]
	v_cmp_lt_u32_e64 s[90:91], 1, v8
	v_add_u32_e32 v73, 1, v71
	s_and_saveexec_b64 s[38:39], s[90:91]
	s_cbranch_execz .LBB0_132
	v_mad_i64_i32 v[14:15], s[92:93], v73, s46, v[2:3]
	global_load_dwordx4 v[10:13], v[14:15], off offset:16
	s_nop 0
	global_load_dwordx4 v[14:17], v[14:15], off
	v_add_co_u32_e32 v18, vcc, 0x3000, v6
	v_lshl_add_u64 v[44:45], v[6:7], 0, s[28:29]
	s_nop 0
	v_addc_co_u32_e32 v19, vcc, 0, v7, vcc
	v_subrev_u32_e32 v248, s100, v18
	v_lshrrev_b32_e32 v249, 12, v248
	v_and_b32_e32 v248, 0xfff, v248
	v_lshl_add_u32 v248, v249, 9, v248
	v_add_u32_e32 v248, 0x1e000, v248
	ds_read_b128 v[18:21], v248
	s_nop 0
	v_subrev_u32_e32 v248, s100, v44
	v_lshrrev_b32_e32 v249, 12, v248
	v_and_b32_e32 v248, 0xfff, v248
	v_lshl_add_u32 v248, v249, 9, v248
	v_add_u32_e32 v248, 0x1e000, v248
	ds_read_b128 v[36:39], v248 offset:48
	v_subrev_u32_e32 v248, s100, v44
	v_lshrrev_b32_e32 v249, 12, v248
	v_and_b32_e32 v248, 0xfff, v248
	v_lshl_add_u32 v248, v249, 9, v248
	v_add_u32_e32 v248, 0x1e000, v248
	ds_read_b128 v[40:43], v248 offset:32
	s_nop 0
	v_subrev_u32_e32 v248, s100, v44
	v_lshrrev_b32_e32 v249, 12, v248
	v_and_b32_e32 v248, 0xfff, v248
	v_lshl_add_u32 v248, v249, 9, v248
	v_add_u32_e32 v248, 0x1e000, v248
	ds_read_b128 v[44:47], v248 offset:16
	s_waitcnt vmcnt(0)
	s_waitcnt lgkmcnt(0)
	v_lshlrev_b32_e32 v48, 16, v14
	v_and_b32_e32 v49, 0xffff0000, v14
	v_lshlrev_b32_e32 v14, 16, v15
	v_and_b32_e32 v15, 0xffff0000, v15
	s_waitcnt vmcnt(0)
	s_waitcnt lgkmcnt(0)
	v_pk_fma_f32 v[24:25], v[20:21], v[14:15], v[24:25]
	v_lshlrev_b32_e32 v14, 16, v16
	v_and_b32_e32 v15, 0xffff0000, v16
	s_waitcnt vmcnt(0)
	s_waitcnt lgkmcnt(0)
	v_pk_fma_f32 v[26:27], v[44:45], v[14:15], v[26:27]
	v_lshlrev_b32_e32 v14, 16, v17
	v_and_b32_e32 v15, 0xffff0000, v17
	v_pk_fma_f32 v[28:29], v[46:47], v[14:15], v[28:29]
	v_lshlrev_b32_e32 v14, 16, v10
	v_and_b32_e32 v15, 0xffff0000, v10
	v_lshlrev_b32_e32 v10, 16, v11
	v_and_b32_e32 v11, 0xffff0000, v11
	v_pk_fma_f32 v[32:33], v[42:43], v[10:11], v[32:33]
	v_lshlrev_b32_e32 v10, 16, v12
	v_and_b32_e32 v11, 0xffff0000, v12
	v_pk_fma_f32 v[34:35], v[36:37], v[10:11], v[34:35]
	v_lshlrev_b32_e32 v10, 16, v13
	v_and_b32_e32 v11, 0xffff0000, v13
	v_pk_fma_f32 v[22:23], v[18:19], v[48:49], v[22:23]
	v_pk_fma_f32 v[30:31], v[40:41], v[14:15], v[30:31]
	v_pk_fma_f32 v[36:37], v[38:39], v[10:11], v[4:5]
.LBB0_132:
	s_or_b64 exec, exec, s[38:39]
	v_cmp_ne_u32_e64 s[92:93], 0, v8
	v_add_u32_e32 v75, 2, v71
	s_and_saveexec_b64 s[38:39], s[92:93]
	s_cbranch_execz .LBB0_134
	v_mad_i64_i32 v[4:5], vcc, v75, s46, v[2:3]
	global_load_dwordx4 v[8:11], v[4:5], off offset:16
	global_load_dwordx4 v[12:15], v[4:5], off
	v_add_co_u32_e32 v16, vcc, 0x6000, v6
	v_lshl_add_u64 v[4:5], v[6:7], 0, s[10:11]
	s_nop 0
	v_addc_co_u32_e32 v17, vcc, 0, v7, vcc
	v_subrev_u32_e32 v248, s100, v16
	v_lshrrev_b32_e32 v249, 12, v248
	v_and_b32_e32 v248, 0xfff, v248
	v_lshl_add_u32 v248, v249, 9, v248
	v_add_u32_e32 v248, 0x1e000, v248
	ds_read_b128 v[16:19], v248
	s_nop 0
	v_subrev_u32_e32 v248, s100, v4
	v_lshrrev_b32_e32 v249, 12, v248
	v_and_b32_e32 v248, 0xfff, v248
	v_lshl_add_u32 v248, v249, 9, v248
	v_add_u32_e32 v248, 0x1e000, v248
	ds_read_b128 v[38:41], v248 offset:48
	v_subrev_u32_e32 v248, s100, v4
	v_lshrrev_b32_e32 v249, 12, v248
	v_and_b32_e32 v248, 0xfff, v248
	v_lshl_add_u32 v248, v249, 9, v248
	v_add_u32_e32 v248, 0x1e000, v248
	ds_read_b128 v[42:45], v248 offset:32
	v_subrev_u32_e32 v248, s100, v4
	v_lshrrev_b32_e32 v249, 12, v248
	v_and_b32_e32 v248, 0xfff, v248
	v_lshl_add_u32 v248, v249, 9, v248
	v_add_u32_e32 v248, 0x1e000, v248
	ds_read_b128 v[46:49], v248 offset:16
	s_waitcnt vmcnt(0)
	s_waitcnt lgkmcnt(0)
	v_lshlrev_b32_e32 v4, 16, v12
	v_and_b32_e32 v5, 0xffff0000, v12
	s_waitcnt vmcnt(0)
	s_waitcnt lgkmcnt(0)
	v_pk_fma_f32 v[22:23], v[16:17], v[4:5], v[22:23]
	v_lshlrev_b32_e32 v4, 16, v13
	v_and_b32_e32 v5, 0xffff0000, v13
	v_pk_fma_f32 v[24:25], v[18:19], v[4:5], v[24:25]
	v_lshlrev_b32_e32 v4, 16, v14
	v_and_b32_e32 v5, 0xffff0000, v14
	s_waitcnt vmcnt(0)
	s_waitcnt lgkmcnt(0)
	v_pk_fma_f32 v[26:27], v[46:47], v[4:5], v[26:27]
	v_lshlrev_b32_e32 v4, 16, v15
	v_and_b32_e32 v5, 0xffff0000, v15
	v_pk_fma_f32 v[28:29], v[48:49], v[4:5], v[28:29]
	v_lshlrev_b32_e32 v4, 16, v8
	v_and_b32_e32 v5, 0xffff0000, v8
	v_pk_fma_f32 v[30:31], v[42:43], v[4:5], v[30:31]
	v_lshlrev_b32_e32 v4, 16, v9
	v_and_b32_e32 v5, 0xffff0000, v9
	v_pk_fma_f32 v[32:33], v[44:45], v[4:5], v[32:33]
	v_lshlrev_b32_e32 v4, 16, v10
	v_and_b32_e32 v5, 0xffff0000, v10
	v_pk_fma_f32 v[34:35], v[38:39], v[4:5], v[34:35]
	v_lshlrev_b32_e32 v4, 16, v11
	v_and_b32_e32 v5, 0xffff0000, v11
	v_pk_fma_f32 v[36:37], v[40:41], v[4:5], v[36:37]
; DI float bflo(u32 w) { return __uint_as_float(w << 16); }
; DI float bfhi(u32 w) { return __uint_as_float(w & 0xffff0000u); }
; DI void phase2(const P& p, char* smem, int bid, int nb) {
;     ...
; #pragma unroll
;       for (int j = 0; j < 4; j++) {
;         int tl = n * 64 + r - 3 + j;
;         if (tl >= 0) {
;           const u16* src = QKV + (size_t)(tok0 + r - 3 + j) * 3072 + col;
;           u32x4 r0 = *(const u32x4*)src, r1 = *(const u32x4*)(src + 8);
;           const float4* cw = (const float4*)(p.conv_w + j * 3072 + col);
;           float4 c0 = cw[0], c1 = cw[1], c2 = cw[2], c3 = cw[3];
;           val[0] += c0.x * bflo(r0[0]); val[1] += c0.y * bfhi(r0[0]); val[2] += c0.z * bflo(r0[1]); val[3] += c0.w * bfhi(r0[1]);
;           val[4] += c1.x * bflo(r0[2]); val[5] += c1.y * bfhi(r0[2]); val[6] += c1.z * bflo(r0[3]); val[7] += c1.w * bfhi(r0[3]);
;           val[8] += c2.x * bflo(r1[0]); val[9] += c2.y * bfhi(r1[0]); val[10] += c2.z * bflo(r1[1]); val[11] += c2.w * bfhi(r1[1]);
;           val[12] += c3.x * bflo(r1[2]); val[13] += c3.y * bfhi(r1[2]); val[14] += c3.z * bflo(r1[3]); val[15] += c3.w * bfhi(r1[3]);
;         }
;       }
;       float ss = 0.f;
; #pragma unroll
;       for (int c = 0; c < 16; c++) { float x = val[c]; x = x / (1.f + __expf(-x)); val[c] = x; ss += x * x; }
.LBB0_134:
	s_or_b64 exec, exec, s[38:39]
	v_add_u32_e32 v52, s40, v63
	v_mad_i64_i32 v[8:9], s[38:39], v52, s46, v[2:3]
	global_load_dwordx4 v[2:5], v[8:9], off offset:16
	global_load_dwordx4 v[14:17], v[8:9], off
	v_lshl_add_u64 v[18:19], v[6:7], 0, s[34:35]
	v_add_co_u32_e32 v6, vcc, 0x9000, v6
	v_mov_b32_e32 v54, 0
	s_nop 0
	v_addc_co_u32_e32 v7, vcc, 0, v7, vcc
	v_subrev_u32_e32 v248, s100, v6
	v_lshrrev_b32_e32 v249, 12, v248
	v_and_b32_e32 v248, 0xfff, v248
	v_lshl_add_u32 v248, v249, 9, v248
	v_add_u32_e32 v248, 0x1e000, v248
	ds_read_b128 v[38:41], v248
	s_nop 0
	v_subrev_u32_e32 v248, s100, v18
	v_lshrrev_b32_e32 v249, 12, v248
	v_and_b32_e32 v248, 0xfff, v248
	v_lshl_add_u32 v248, v249, 9, v248
	v_add_u32_e32 v248, 0x1e000, v248
	ds_read_b128 v[6:9], v248 offset:48
	v_subrev_u32_e32 v248, s100, v18
	v_lshrrev_b32_e32 v249, 12, v248
	v_and_b32_e32 v248, 0xfff, v248
	v_lshl_add_u32 v248, v249, 9, v248
	v_add_u32_e32 v248, 0x1e000, v248
	ds_read_b128 v[10:13], v248 offset:32
	s_nop 0
	v_subrev_u32_e32 v248, s100, v18
	v_lshrrev_b32_e32 v249, 12, v248
	v_and_b32_e32 v248, 0xfff, v248
	v_lshl_add_u32 v248, v249, 9, v248
	v_add_u32_e32 v248, 0x1e000, v248
	ds_read_b128 v[18:21], v248 offset:16
	v_mov_b32_e32 v46, 0
	v_mov_b32_e32 v47, 0
	s_waitcnt vmcnt(0)
	s_waitcnt lgkmcnt(0)
	v_lshlrev_b32_e32 v42, 16, v14
	v_and_b32_e32 v43, 0xffff0000, v14
	s_waitcnt vmcnt(0)
	s_waitcnt lgkmcnt(0)
	v_pk_fma_f32 v[22:23], v[38:39], v[42:43], v[22:23]
	s_nop 0
	v_mul_f32_e32 v14, 0xbfb8aa3b, v22
	v_exp_f32_e32 v38, v14
	v_mul_f32_e32 v14, 0xbfb8aa3b, v23
	v_exp_f32_e32 v39, v14
	s_nop 0
	v_pk_add_f32 v[38:39], v[38:39], 1.0 op_sel_hi:[1,0]
	s_nop 0
	v_div_scale_f32 v14, s[38:39], v39, v39, v23
	v_rcp_f32_e32 v42, v14
	s_nop 0
	v_fma_f32 v43, -v14, v42, 1.0
	v_fmac_f32_e32 v42, v43, v42
	v_div_scale_f32 v43, vcc, v23, v39, v23
	v_mul_f32_e32 v44, v43, v42
	v_fma_f32 v45, -v14, v44, v43
	v_fmac_f32_e32 v44, v45, v42
	v_fma_f32 v14, -v14, v44, v43
	v_div_fmas_f32 v14, v14, v42, v44
	v_div_fixup_f32 v23, v14, v39, v23
	v_div_scale_f32 v14, s[38:39], v38, v38, v22
	v_rcp_f32_e32 v39, v14
	s_nop 0
	v_fma_f32 v42, -v14, v39, 1.0
	v_fmac_f32_e32 v39, v42, v39
	v_div_scale_f32 v42, vcc, v22, v38, v22
	v_mul_f32_e32 v43, v42, v39
	v_fma_f32 v44, -v14, v43, v42
	v_fmac_f32_e32 v43, v44, v39
	v_fma_f32 v14, -v14, v43, v42
	v_div_fmas_f32 v14, v14, v39, v43
	v_div_fixup_f32 v22, v14, v38, v22
	v_lshlrev_b32_e32 v14, 16, v15
	v_and_b32_e32 v15, 0xffff0000, v15
	v_pk_fma_f32 v[14:15], v[40:41], v[14:15], v[24:25]
	v_pk_mul_f32 v[38:39], v[22:23], v[22:23]
	v_mul_f32_e32 v24, 0xbfb8aa3b, v14
	v_mul_f32_e32 v25, 0xbfb8aa3b, v15
	v_exp_f32_e32 v24, v24
	v_exp_f32_e32 v25, v25
	s_nop 0
	v_pk_add_f32 v[24:25], v[24:25], 1.0 op_sel_hi:[1,0]
	s_nop 0
	v_div_scale_f32 v40, s[38:39], v25, v25, v15
	v_rcp_f32_e32 v41, v40
	s_nop 0
	v_fma_f32 v42, -v40, v41, 1.0
	v_fmac_f32_e32 v41, v42, v41
	v_div_scale_f32 v42, vcc, v15, v25, v15
	v_mul_f32_e32 v43, v42, v41
	v_fma_f32 v44, -v40, v43, v42
	v_fmac_f32_e32 v43, v44, v41
	v_fma_f32 v40, -v40, v43, v42
	v_div_fmas_f32 v40, v40, v41, v43
	v_div_fixup_f32 v25, v40, v25, v15
	v_div_scale_f32 v15, s[38:39], v24, v24, v14
	v_rcp_f32_e32 v40, v15
	s_nop 0
	v_fma_f32 v41, -v15, v40, 1.0
	v_fmac_f32_e32 v40, v41, v40
	v_div_scale_f32 v41, vcc, v14, v24, v14
	v_mul_f32_e32 v42, v41, v40
	v_fma_f32 v43, -v15, v42, v41
	v_fmac_f32_e32 v42, v43, v40
	v_fma_f32 v15, -v15, v42, v41
	v_div_fmas_f32 v15, v15, v40, v42
	v_lshlrev_b32_e32 v40, 16, v16
	v_and_b32_e32 v41, 0xffff0000, v16
	s_waitcnt vmcnt(0)
	s_waitcnt lgkmcnt(0)
	v_pk_fma_f32 v[18:19], v[18:19], v[40:41], v[26:27]
	v_div_fixup_f32 v24, v15, v24, v14
	v_mul_f32_e32 v16, 0xbfb8aa3b, v18
	v_exp_f32_e32 v26, v16
	v_mul_f32_e32 v16, 0xbfb8aa3b, v19
	v_exp_f32_e32 v27, v16
	v_pk_mul_f32 v[14:15], v[24:25], v[24:25]
	v_pk_add_f32 v[26:27], v[26:27], 1.0 op_sel_hi:[1,0]
	s_nop 0
	v_div_scale_f32 v16, s[38:39], v27, v27, v19
	v_rcp_f32_e32 v40, v16
	s_nop 0
	v_fma_f32 v41, -v16, v40, 1.0
	v_fmac_f32_e32 v40, v41, v40
	v_div_scale_f32 v41, vcc, v19, v27, v19
	v_mul_f32_e32 v42, v41, v40
	v_fma_f32 v43, -v16, v42, v41
	v_fmac_f32_e32 v42, v43, v40
	v_fma_f32 v16, -v16, v42, v41
	v_div_fmas_f32 v16, v16, v40, v42
	v_div_fixup_f32 v27, v16, v27, v19
	v_div_scale_f32 v16, s[38:39], v26, v26, v18
	v_rcp_f32_e32 v19, v16
	s_nop 0
	v_fma_f32 v40, -v16, v19, 1.0
	v_fmac_f32_e32 v19, v40, v19
	v_div_scale_f32 v40, vcc, v18, v26, v18
	v_mul_f32_e32 v41, v40, v19
	v_fma_f32 v42, -v16, v41, v40
	v_fmac_f32_e32 v41, v42, v19
	v_fma_f32 v16, -v16, v41, v40
	v_div_fmas_f32 v16, v16, v19, v41
	v_div_fixup_f32 v26, v16, v26, v18
	v_lshlrev_b32_e32 v16, 16, v17
	v_and_b32_e32 v17, 0xffff0000, v17
	v_pk_fma_f32 v[16:17], v[20:21], v[16:17], v[28:29]
	v_pk_mul_f32 v[18:19], v[26:27], v[26:27]
	v_mul_f32_e32 v20, 0xbfb8aa3b, v16
	v_mul_f32_e32 v21, 0xbfb8aa3b, v17
	v_exp_f32_e32 v20, v20
	v_exp_f32_e32 v21, v21
	s_nop 0
	v_pk_add_f32 v[20:21], v[20:21], 1.0 op_sel_hi:[1,0]
	s_nop 0
	v_div_scale_f32 v28, s[38:39], v21, v21, v17
	v_rcp_f32_e32 v29, v28
	s_nop 0
	v_fma_f32 v40, -v28, v29, 1.0
	v_fmac_f32_e32 v29, v40, v29
	v_div_scale_f32 v40, vcc, v17, v21, v17
	v_mul_f32_e32 v41, v40, v29
	v_fma_f32 v42, -v28, v41, v40
	v_fmac_f32_e32 v41, v42, v29
	v_fma_f32 v28, -v28, v41, v40
	v_div_fmas_f32 v28, v28, v29, v41
	v_div_fixup_f32 v29, v28, v21, v17
	v_div_scale_f32 v17, s[38:39], v20, v20, v16
	v_rcp_f32_e32 v21, v17
	s_nop 0
	v_fma_f32 v28, -v17, v21, 1.0
	v_fmac_f32_e32 v21, v28, v21
	v_div_scale_f32 v28, vcc, v16, v20, v16
	v_mul_f32_e32 v40, v28, v21
	v_fma_f32 v41, -v17, v40, v28
	v_fmac_f32_e32 v40, v41, v21
; DI void phase2(const P& p, char* smem, int bid, int nb) {
;     ...
;       float ss = 0.f;
; #pragma unroll
;       for (int c = 0; c < 16; c++) { float x = val[c]; x = x / (1.f + __expf(-x)); val[c] = x; ss += x * x; }
;       if (mat < 2) {
;         ss += __shfl_xor(ss, 1); ss += __shfl_xor(ss, 2); ss += __shfl_xor(ss, 4);
;         float rinv = rsqrtf(ss + RMS_EPS) * (mat == 0 ? 0.08838834764831845f : 1.f);
; #pragma unroll
;         for (int c = 0; c < 16; c++) val[c] *= rinv;
;       }
; #pragma unroll
;       for (int c = 0; c < 16; c++) { if (mat == 0) qv[c] = val[c]; else if (mat == 1) kv[c] = val[c]; else vv[c] = val[c]; }
	v_fma_f32 v17, -v17, v40, v28
	v_div_fmas_f32 v17, v17, v21, v40
	v_div_fixup_f32 v28, v17, v20, v16
	v_lshlrev_b32_e32 v20, 16, v2
	v_and_b32_e32 v21, 0xffff0000, v2
	v_pk_fma_f32 v[10:11], v[10:11], v[20:21], v[30:31]
	v_pk_mul_f32 v[16:17], v[28:29], v[28:29]
	v_mul_f32_e32 v2, 0xbfb8aa3b, v10
	v_exp_f32_e32 v20, v2
	v_mul_f32_e32 v2, 0xbfb8aa3b, v11
	v_exp_f32_e32 v21, v2
	s_nop 0
	v_pk_add_f32 v[20:21], v[20:21], 1.0 op_sel_hi:[1,0]
	s_nop 0
	v_div_scale_f32 v2, s[38:39], v21, v21, v11
	v_rcp_f32_e32 v30, v2
	s_nop 0
	v_fma_f32 v31, -v2, v30, 1.0
	v_fmac_f32_e32 v30, v31, v30
	v_div_scale_f32 v31, vcc, v11, v21, v11
	v_mul_f32_e32 v40, v31, v30
	v_fma_f32 v41, -v2, v40, v31
	v_fmac_f32_e32 v40, v41, v30
	v_fma_f32 v2, -v2, v40, v31
	v_div_fmas_f32 v2, v2, v30, v40
	v_div_fixup_f32 v31, v2, v21, v11
	v_div_scale_f32 v2, s[38:39], v20, v20, v10
	v_rcp_f32_e32 v11, v2
	v_mov_b32_e32 v41, 0
	v_fma_f32 v21, -v2, v11, 1.0
	v_fmac_f32_e32 v11, v21, v11
	v_div_scale_f32 v21, vcc, v10, v20, v10
	v_mul_f32_e32 v30, v21, v11
	v_fma_f32 v40, -v2, v30, v21
	v_fmac_f32_e32 v30, v40, v11
	v_fma_f32 v2, -v2, v30, v21
	v_div_fmas_f32 v2, v2, v11, v30
	v_div_fixup_f32 v30, v2, v20, v10
	v_lshlrev_b32_e32 v2, 16, v3
	v_and_b32_e32 v3, 0xffff0000, v3
	v_pk_fma_f32 v[2:3], v[12:13], v[2:3], v[32:33]
	v_pk_mul_f32 v[10:11], v[30:31], v[30:31]
	v_mul_f32_e32 v12, 0xbfb8aa3b, v2
	v_mul_f32_e32 v13, 0xbfb8aa3b, v3
	v_exp_f32_e32 v12, v12
	v_exp_f32_e32 v13, v13
	s_nop 0
	v_pk_add_f32 v[12:13], v[12:13], 1.0 op_sel_hi:[1,0]
	s_nop 0
	v_div_scale_f32 v20, s[38:39], v13, v13, v3
	v_rcp_f32_e32 v21, v20
	s_nop 0
	v_fma_f32 v32, -v20, v21, 1.0
	v_fmac_f32_e32 v21, v32, v21
	v_div_scale_f32 v32, vcc, v3, v13, v3
	v_mul_f32_e32 v33, v32, v21
	v_fma_f32 v40, -v20, v33, v32
	v_fmac_f32_e32 v33, v40, v21
	v_fma_f32 v20, -v20, v33, v32
	v_div_fmas_f32 v20, v20, v21, v33
	v_div_fixup_f32 v33, v20, v13, v3
	v_div_scale_f32 v3, s[38:39], v12, v12, v2
	v_rcp_f32_e32 v13, v3
	v_mov_b32_e32 v40, 0
	v_fma_f32 v20, -v3, v13, 1.0
	v_fmac_f32_e32 v13, v20, v13
	v_div_scale_f32 v20, vcc, v2, v12, v2
	v_mul_f32_e32 v21, v20, v13
	v_fma_f32 v32, -v3, v21, v20
	v_fmac_f32_e32 v21, v32, v13
	v_fma_f32 v3, -v3, v21, v20
	v_div_fmas_f32 v3, v3, v13, v21
	v_div_fixup_f32 v32, v3, v12, v2
	v_lshlrev_b32_e32 v12, 16, v4
	v_and_b32_e32 v13, 0xffff0000, v4
	v_pk_fma_f32 v[6:7], v[6:7], v[12:13], v[34:35]
	v_pk_mul_f32 v[2:3], v[32:33], v[32:33]
	v_mul_f32_e32 v4, 0xbfb8aa3b, v6
	v_exp_f32_e32 v12, v4
	v_mul_f32_e32 v4, 0xbfb8aa3b, v7
	v_exp_f32_e32 v13, v4
	s_nop 0
	v_pk_add_f32 v[12:13], v[12:13], 1.0 op_sel_hi:[1,0]
	s_nop 0
	v_div_scale_f32 v4, s[38:39], v13, v13, v7
	v_rcp_f32_e32 v20, v4
	s_nop 0
	v_fma_f32 v21, -v4, v20, 1.0
	v_fmac_f32_e32 v20, v21, v20
	v_div_scale_f32 v21, vcc, v7, v13, v7
	v_mul_f32_e32 v34, v21, v20
	v_fma_f32 v35, -v4, v34, v21
	v_fmac_f32_e32 v34, v35, v20
	v_fma_f32 v4, -v4, v34, v21
	v_div_fmas_f32 v4, v4, v20, v34
	v_div_fixup_f32 v35, v4, v13, v7
	v_div_scale_f32 v4, s[38:39], v12, v12, v6
	v_rcp_f32_e32 v7, v4
	s_nop 0
	v_fma_f32 v13, -v4, v7, 1.0
	v_fmac_f32_e32 v7, v13, v7
	v_div_scale_f32 v13, vcc, v6, v12, v6
	v_mul_f32_e32 v20, v13, v7
	v_fma_f32 v21, -v4, v20, v13
	v_fmac_f32_e32 v20, v21, v7
	v_fma_f32 v4, -v4, v20, v13
	v_div_fmas_f32 v4, v4, v7, v20
	v_div_fixup_f32 v34, v4, v12, v6
	v_lshlrev_b32_e32 v4, 16, v5
	v_and_b32_e32 v5, 0xffff0000, v5
	v_pk_fma_f32 v[4:5], v[8:9], v[4:5], v[36:37]
	v_pk_mul_f32 v[6:7], v[34:35], v[34:35]
	v_mul_f32_e32 v8, 0xbfb8aa3b, v4
	v_mul_f32_e32 v9, 0xbfb8aa3b, v5
	v_exp_f32_e32 v8, v8
	v_exp_f32_e32 v9, v9
	s_nop 0
	v_pk_add_f32 v[8:9], v[8:9], 1.0 op_sel_hi:[1,0]
	s_nop 0
	v_div_scale_f32 v12, s[38:39], v9, v9, v5
	v_rcp_f32_e32 v13, v12
	s_nop 0
	v_fma_f32 v20, -v12, v13, 1.0
	v_fmac_f32_e32 v13, v20, v13
	v_div_scale_f32 v20, vcc, v5, v9, v5
	v_mul_f32_e32 v21, v20, v13
	v_fma_f32 v36, -v12, v21, v20
	v_fmac_f32_e32 v21, v36, v13
	v_fma_f32 v12, -v12, v21, v20
	v_div_fmas_f32 v12, v12, v13, v21
	v_div_fixup_f32 v37, v12, v9, v5
	v_div_scale_f32 v5, s[38:39], v8, v8, v4
	v_rcp_f32_e32 v9, v5
	s_nop 0
	v_fma_f32 v12, -v5, v9, 1.0
	v_fmac_f32_e32 v9, v12, v9
	v_div_scale_f32 v12, vcc, v4, v8, v4
	v_mul_f32_e32 v13, v12, v9
	v_fma_f32 v20, -v5, v13, v12
	v_fmac_f32_e32 v13, v20, v9
	v_fma_f32 v5, -v5, v13, v12
	v_div_fmas_f32 v5, v5, v9, v13
	v_div_fixup_f32 v36, v5, v8, v4
	v_add_f32_e32 v8, v38, v39
	v_add_f32_e32 v8, v14, v8
	v_add_f32_e32 v8, v15, v8
	v_add_f32_e32 v8, v18, v8
	v_add_f32_e32 v8, v19, v8
	v_add_f32_e32 v8, v16, v8
	v_add_f32_e32 v8, v17, v8
	v_add_f32_e32 v8, v8, v10
	v_add_f32_e32 v8, v11, v8
	v_add_f32_e32 v2, v2, v8
	v_add_f32_e32 v2, v3, v2
	v_add_f32_e32 v2, v6, v2
	v_pk_mul_f32 v[4:5], v[36:37], v[36:37]
	v_add_f32_e32 v2, v7, v2
	v_add_f32_e32 v2, v4, v2
	v_add_f32_e32 v2, v5, v2
	ds_bpermute_b32 v3, v185, v2
	s_waitcnt lgkmcnt(0)
	v_add_f32_e32 v2, v2, v3
	ds_bpermute_b32 v3, v186, v2
	s_waitcnt lgkmcnt(0)
	v_add_f32_e32 v79, v2, v3
	ds_bpermute_b32 v81, v188, v79
	v_or_b32_e32 v3, 0x400, v77
	v_lshlrev_b32_e32 v60, 2, v3
	v_mov_b32_e32 v2, 0
	v_lshl_add_u64 v[6:7], s[30:31], 0, v[60:61]
	v_lshlrev_b32_e32 v60, 1, v3
	v_mov_b32_e32 v3, 0
	v_mov_b32_e32 v55, v2
	v_mov_b32_e32 v56, v2
	v_mov_b32_e32 v57, v2
	v_mov_b32_e32 v50, v2
	v_mov_b32_e32 v51, v2
	v_mov_b32_e32 v48, v2
	v_mov_b32_e32 v49, v2
	v_mov_b32_e32 v44, v2
	v_mov_b32_e32 v45, v2
	v_mov_b32_e32 v42, v2
	v_mov_b32_e32 v43, v2
	s_and_saveexec_b64 s[38:39], s[88:89]
	s_cbranch_execz .LBB0_148
; DI float bflo(u32 w) { return __uint_as_float(w << 16); }
; DI float bfhi(u32 w) { return __uint_as_float(w & 0xffff0000u); }
; DI void phase2(const P& p, char* smem, int bid, int nb) {
;     ...
;     for (int mat = 0; mat < 3; mat++) {
;       float val[16];
; #pragma unroll
;       for (int c = 0; c < 16; c++) val[c] = 0.f;
;       const int col = mat * 1024 + h * 128 + seg * 16;
; #pragma unroll
;       for (int j = 0; j < 4; j++) {
;         int tl = n * 64 + r - 3 + j;
;         if (tl >= 0) {
;           const u16* src = QKV + (size_t)(tok0 + r - 3 + j) * 3072 + col;
;           u32x4 r0 = *(const u32x4*)src, r1 = *(const u32x4*)(src + 8);
;           const float4* cw = (const float4*)(p.conv_w + j * 3072 + col);
;           float4 c0 = cw[0], c1 = cw[1], c2 = cw[2], c3 = cw[3];
;           val[0] += c0.x * bflo(r0[0]); val[1] += c0.y * bfhi(r0[0]); val[2] += c0.z * bflo(r0[1]); val[3] += c0.w * bfhi(r0[1]);
;           val[4] += c1.x * bflo(r0[2]); val[5] += c1.y * bfhi(r0[2]); val[6] += c1.z * bflo(r0[3]); val[7] += c1.w * bfhi(r0[3]);
;           val[8] += c2.x * bflo(r1[0]); val[9] += c2.y * bfhi(r1[0]); val[10] += c2.z * bflo(r1[1]); val[11] += c2.w * bfhi(r1[1]);
;           val[12] += c3.x * bflo(r1[2]); val[13] += c3.y * bfhi(r1[2]); val[14] += c3.z * bflo(r1[3]); val[15] += c3.w * bfhi(r1[3]);
;         }
	v_mov_b64_e32 v[2:3], s[16:17]
	v_mad_i64_i32 v[2:3], s[40:41], v71, s46, v[2:3]
	v_lshl_add_u64 v[8:9], v[2:3], 0, v[60:61]
	global_load_dwordx4 v[2:5], v[8:9], off offset:16
	s_nop 0
	global_load_dwordx4 v[8:11], v[8:9], off
	s_nop 0
	v_subrev_u32_e32 v248, s100, v6
	v_lshrrev_b32_e32 v249, 12, v248
	v_and_b32_e32 v248, 0xfff, v248
	v_lshl_add_u32 v248, v249, 9, v248
	v_add_u32_e32 v248, 0x1e000, v248
	ds_read_b128 v[12:15], v248 offset:48
	v_subrev_u32_e32 v248, s100, v6
	v_lshrrev_b32_e32 v249, 12, v248
	v_and_b32_e32 v248, 0xfff, v248
	v_lshl_add_u32 v248, v249, 9, v248
	v_add_u32_e32 v248, 0x1e000, v248
	ds_read_b128 v[16:19], v248 offset:32
	v_subrev_u32_e32 v248, s100, v6
	v_lshrrev_b32_e32 v249, 12, v248
	v_and_b32_e32 v248, 0xfff, v248
	v_lshl_add_u32 v248, v249, 9, v248
	v_add_u32_e32 v248, 0x1e000, v248
	ds_read_b128 v[42:45], v248 offset:16
	v_subrev_u32_e32 v248, s100, v6
	v_lshrrev_b32_e32 v249, 12, v248
	v_and_b32_e32 v248, 0xfff, v248
	v_lshl_add_u32 v248, v249, 9, v248
	v_add_u32_e32 v248, 0x1e000, v248
	ds_read_b128 v[46:49], v248
	s_waitcnt vmcnt(0)
	s_waitcnt lgkmcnt(0)
	v_lshlrev_b32_e32 v20, 16, v8
	v_and_b32_e32 v21, 0xffff0000, v8
	v_lshlrev_b32_e32 v8, 16, v9
	v_and_b32_e32 v9, 0xffff0000, v9
	s_waitcnt vmcnt(0)
	s_waitcnt lgkmcnt(0)
	v_pk_fma_f32 v[54:55], v[48:49], v[8:9], 0 op_sel_hi:[1,1,0]
	v_lshlrev_b32_e32 v8, 16, v10
	v_and_b32_e32 v9, 0xffff0000, v10
	v_pk_fma_f32 v[56:57], v[42:43], v[8:9], 0 op_sel_hi:[1,1,0]
	v_lshlrev_b32_e32 v8, 16, v11
	v_and_b32_e32 v9, 0xffff0000, v11
	v_pk_fma_f32 v[50:51], v[44:45], v[8:9], 0 op_sel_hi:[1,1,0]
	v_lshlrev_b32_e32 v8, 16, v2
	v_and_b32_e32 v9, 0xffff0000, v2
	v_lshlrev_b32_e32 v2, 16, v3
	v_and_b32_e32 v3, 0xffff0000, v3
	v_pk_fma_f32 v[44:45], v[18:19], v[2:3], 0 op_sel_hi:[1,1,0]
	v_lshlrev_b32_e32 v2, 16, v4
	v_and_b32_e32 v3, 0xffff0000, v4
	v_pk_fma_f32 v[42:43], v[12:13], v[2:3], 0 op_sel_hi:[1,1,0]
	v_lshlrev_b32_e32 v2, 16, v5
	v_and_b32_e32 v3, 0xffff0000, v5
	v_pk_fma_f32 v[2:3], v[14:15], v[2:3], 0 op_sel_hi:[1,1,0]
	v_pk_fma_f32 v[40:41], v[46:47], v[20:21], 0 op_sel_hi:[1,1,0]
	v_pk_fma_f32 v[48:49], v[16:17], v[8:9], 0 op_sel_hi:[1,1,0]
	v_mov_b32_e32 v46, v2
	v_mov_b32_e32 v47, v3
	s_or_b64 exec, exec, s[38:39]
	s_and_saveexec_b64 s[38:39], s[90:91]
	s_cbranch_execnz .LBB0_149

; DI float bflo(u32 w) { return __uint_as_float(w << 16); }
; DI float bfhi(u32 w) { return __uint_as_float(w & 0xffff0000u); }
; DI void phase2(const P& p, char* smem, int bid, int nb) {
;     ...
; #pragma unroll
;       for (int j = 0; j < 4; j++) {
;         int tl = n * 64 + r - 3 + j;
;         if (tl >= 0) {
;           const u16* src = QKV + (size_t)(tok0 + r - 3 + j) * 3072 + col;
;           u32x4 r0 = *(const u32x4*)src, r1 = *(const u32x4*)(src + 8);
;           const float4* cw = (const float4*)(p.conv_w + j * 3072 + col);
;           float4 c0 = cw[0], c1 = cw[1], c2 = cw[2], c3 = cw[3];
;           val[0] += c0.x * bflo(r0[0]); val[1] += c0.y * bfhi(r0[0]); val[2] += c0.z * bflo(r0[1]); val[3] += c0.w * bfhi(r0[1]);
;           val[4] += c1.x * bflo(r0[2]); val[5] += c1.y * bfhi(r0[2]); val[6] += c1.z * bflo(r0[3]); val[7] += c1.w * bfhi(r0[3]);
;           val[8] += c2.x * bflo(r1[0]); val[9] += c2.y * bfhi(r1[0]); val[10] += c2.z * bflo(r1[1]); val[11] += c2.w * bfhi(r1[1]);
;           val[12] += c3.x * bflo(r1[2]); val[13] += c3.y * bfhi(r1[2]); val[14] += c3.z * bflo(r1[3]); val[15] += c3.w * bfhi(r1[3]);
;         }
;       }
;       float ss = 0.f;
; #pragma unroll
;       for (int c = 0; c < 16; c++) { float x = val[c]; x = x / (1.f + __expf(-x)); val[c] = x; ss += x * x; }
.LBB0_137:
	v_mov_b64_e32 v[2:3], s[16:17]
	v_mad_i64_i32 v[2:3], s[40:41], v75, s46, v[2:3]
	v_lshl_add_u64 v[8:9], v[2:3], 0, v[60:61]
	s_movk_i32 s37, 0x6000
	global_load_dwordx4 v[2:5], v[8:9], off offset:16
	s_nop 0
	global_load_dwordx4 v[8:11], v[8:9], off
	v_add_co_u32_e32 v12, vcc, s37, v6
	v_lshl_add_u64 v[20:21], v[6:7], 0, s[10:11]
	s_nop 0
	v_addc_co_u32_e32 v13, vcc, 0, v7, vcc
	v_subrev_u32_e32 v248, s100, v12
	v_lshrrev_b32_e32 v249, 12, v248
	v_and_b32_e32 v248, 0xfff, v248
	v_lshl_add_u32 v248, v249, 9, v248
	v_add_u32_e32 v248, 0x1e000, v248
	ds_read_b128 v[12:15], v248
	s_nop 0
	v_subrev_u32_e32 v248, s100, v20
	v_lshrrev_b32_e32 v249, 12, v248
	v_and_b32_e32 v248, 0xfff, v248
	v_lshl_add_u32 v248, v249, 9, v248
	v_add_u32_e32 v248, 0x1e000, v248
	ds_read_b128 v[16:19], v248 offset:48
	v_subrev_u32_e32 v248, s100, v20
	v_lshrrev_b32_e32 v249, 12, v248
	v_and_b32_e32 v248, 0xfff, v248
	v_lshl_add_u32 v248, v249, 9, v248
	v_add_u32_e32 v248, 0x1e000, v248
	ds_read_b128 v[82:85], v248 offset:32
	v_subrev_u32_e32 v248, s100, v20
	v_lshrrev_b32_e32 v249, 12, v248
	v_and_b32_e32 v248, 0xfff, v248
	v_lshl_add_u32 v248, v249, 9, v248
	v_add_u32_e32 v248, 0x1e000, v248
	ds_read_b128 v[86:89], v248 offset:16
	s_waitcnt vmcnt(0)
	s_waitcnt lgkmcnt(0)
	v_lshlrev_b32_e32 v20, 16, v8
	v_and_b32_e32 v21, 0xffff0000, v8
	v_lshlrev_b32_e32 v8, 16, v9
	v_and_b32_e32 v9, 0xffff0000, v9
	s_waitcnt vmcnt(0)
	s_waitcnt lgkmcnt(0)
	v_pk_fma_f32 v[54:55], v[14:15], v[8:9], v[54:55]
	v_lshlrev_b32_e32 v8, 16, v10
	v_and_b32_e32 v9, 0xffff0000, v10
	s_waitcnt vmcnt(0)
	s_waitcnt lgkmcnt(0)
	v_pk_fma_f32 v[56:57], v[86:87], v[8:9], v[56:57]
	v_lshlrev_b32_e32 v8, 16, v11
	v_and_b32_e32 v9, 0xffff0000, v11
	v_pk_fma_f32 v[50:51], v[88:89], v[8:9], v[50:51]
	v_lshlrev_b32_e32 v8, 16, v2
	v_and_b32_e32 v9, 0xffff0000, v2
	v_lshlrev_b32_e32 v2, 16, v3
	v_and_b32_e32 v3, 0xffff0000, v3
	v_pk_fma_f32 v[44:45], v[84:85], v[2:3], v[44:45]
	v_lshlrev_b32_e32 v2, 16, v4
	v_and_b32_e32 v3, 0xffff0000, v4
	v_pk_fma_f32 v[42:43], v[16:17], v[2:3], v[42:43]
	v_lshlrev_b32_e32 v2, 16, v5
	v_and_b32_e32 v3, 0xffff0000, v5
	v_pk_fma_f32 v[40:41], v[12:13], v[20:21], v[40:41]
	v_pk_fma_f32 v[48:49], v[82:83], v[8:9], v[48:49]
	v_pk_fma_f32 v[46:47], v[18:19], v[2:3], v[46:47]
.LBB0_138:
	s_or_b64 exec, exec, s[38:39]
	v_mad_i64_i32 v[38:39], s[38:39], v52, s46, 0
	v_lshl_add_u64 v[2:3], s[16:17], 0, v[38:39]
	v_lshl_add_u64 v[8:9], v[2:3], 0, v[60:61]
	global_load_dwordx4 v[2:5], v[8:9], off offset:16
	global_load_dwordx4 v[14:17], v[8:9], off
	v_lshl_add_u64 v[18:19], v[6:7], 0, s[34:35]
	v_add_co_u32_e32 v6, vcc, s47, v6
	v_mov_b32_e32 v100, 0
	s_nop 0
	v_addc_co_u32_e32 v7, vcc, 0, v7, vcc
	v_subrev_u32_e32 v248, s100, v6
	v_lshrrev_b32_e32 v249, 12, v248
	v_and_b32_e32 v248, 0xfff, v248
	v_lshl_add_u32 v248, v249, 9, v248
	v_add_u32_e32 v248, 0x1e000, v248
	ds_read_b128 v[82:85], v248
	s_nop 0
	v_subrev_u32_e32 v248, s100, v18
	v_lshrrev_b32_e32 v249, 12, v248
	v_and_b32_e32 v248, 0xfff, v248
	v_lshl_add_u32 v248, v249, 9, v248
	v_add_u32_e32 v248, 0x1e000, v248
	ds_read_b128 v[6:9], v248 offset:48
	v_subrev_u32_e32 v248, s100, v18
	v_lshrrev_b32_e32 v249, 12, v248
	v_and_b32_e32 v248, 0xfff, v248
	v_lshl_add_u32 v248, v249, 9, v248
	v_add_u32_e32 v248, 0x1e000, v248
	ds_read_b128 v[10:13], v248 offset:32
	s_nop 0
	v_subrev_u32_e32 v248, s100, v18
	v_lshrrev_b32_e32 v249, 12, v248
	v_and_b32_e32 v248, 0xfff, v248
	v_lshl_add_u32 v248, v249, 9, v248
	v_add_u32_e32 v248, 0x1e000, v248
	ds_read_b128 v[18:21], v248 offset:16
	v_mov_b32_e32 v101, 0
	v_mov_b32_e32 v98, 0
	s_waitcnt vmcnt(0)
	s_waitcnt lgkmcnt(0)
	v_lshlrev_b32_e32 v52, 16, v14
	v_and_b32_e32 v53, 0xffff0000, v14
	s_waitcnt vmcnt(0)
	s_waitcnt lgkmcnt(0)
	v_pk_fma_f32 v[40:41], v[82:83], v[52:53], v[40:41]
	s_nop 0
	v_mul_f32_e32 v14, 0xbfb8aa3b, v40
	v_exp_f32_e32 v52, v14
	v_mul_f32_e32 v14, 0xbfb8aa3b, v41
	v_exp_f32_e32 v53, v14
	s_nop 0
	v_pk_add_f32 v[52:53], v[52:53], 1.0 op_sel_hi:[1,0]
	s_nop 0
	v_div_scale_f32 v14, s[38:39], v53, v53, v41
	v_rcp_f32_e32 v60, v14
	s_nop 0
	v_fma_f32 v82, -v14, v60, 1.0
	v_fmac_f32_e32 v60, v82, v60
	v_div_scale_f32 v82, vcc, v41, v53, v41
	v_mul_f32_e32 v83, v82, v60
	v_fma_f32 v86, -v14, v83, v82
	v_fmac_f32_e32 v83, v86, v60
	v_fma_f32 v14, -v14, v83, v82
	v_div_fmas_f32 v14, v14, v60, v83
	v_div_fixup_f32 v41, v14, v53, v41
	v_div_scale_f32 v14, s[38:39], v52, v52, v40
	v_rcp_f32_e32 v53, v14
	s_nop 0
	v_fma_f32 v60, -v14, v53, 1.0
	v_fmac_f32_e32 v53, v60, v53
	v_div_scale_f32 v60, vcc, v40, v52, v40
	v_mul_f32_e32 v82, v60, v53
	v_fma_f32 v83, -v14, v82, v60
	v_fmac_f32_e32 v82, v83, v53
	v_fma_f32 v14, -v14, v82, v60
	v_div_fmas_f32 v14, v14, v53, v82
	v_div_fixup_f32 v40, v14, v52, v40
	v_lshlrev_b32_e32 v14, 16, v15
	v_and_b32_e32 v15, 0xffff0000, v15
	v_pk_fma_f32 v[14:15], v[84:85], v[14:15], v[54:55]
	v_pk_mul_f32 v[52:53], v[40:41], v[40:41]
	v_mul_f32_e32 v54, 0xbfb8aa3b, v14
	v_mul_f32_e32 v55, 0xbfb8aa3b, v15
	v_exp_f32_e32 v54, v54
	v_exp_f32_e32 v55, v55
	s_nop 0
	v_pk_add_f32 v[54:55], v[54:55], 1.0 op_sel_hi:[1,0]
	s_nop 0
	v_div_scale_f32 v60, s[38:39], v55, v55, v15
	v_rcp_f32_e32 v82, v60
	s_nop 0
	v_fma_f32 v83, -v60, v82, 1.0
	v_fmac_f32_e32 v82, v83, v82
	v_div_scale_f32 v83, vcc, v15, v55, v15
	v_mul_f32_e32 v84, v83, v82
	v_fma_f32 v85, -v60, v84, v83
	v_fmac_f32_e32 v84, v85, v82
	v_fma_f32 v60, -v60, v84, v83
	v_div_fmas_f32 v60, v60, v82, v84
	v_div_fixup_f32 v15, v60, v55, v15
	v_div_scale_f32 v55, s[38:39], v54, v54, v14
	v_rcp_f32_e32 v60, v55
	s_nop 0
	v_fma_f32 v82, -v55, v60, 1.0
	v_fmac_f32_e32 v60, v82, v60
	v_div_scale_f32 v82, vcc, v14, v54, v14
	v_mul_f32_e32 v83, v82, v60
	v_fma_f32 v84, -v55, v83, v82
	v_fmac_f32_e32 v83, v84, v60
	v_fma_f32 v55, -v55, v83, v82
	v_div_fmas_f32 v55, v55, v60, v83
	v_lshlrev_b32_e32 v82, 16, v16
	v_and_b32_e32 v83, 0xffff0000, v16
	s_waitcnt vmcnt(0)
; DI void phase2(const P& p, char* smem, int bid, int nb) {
;     ...
;       float ss = 0.f;
; #pragma unroll
;       for (int c = 0; c < 16; c++) { float x = val[c]; x = x / (1.f + __expf(-x)); val[c] = x; ss += x * x; }
;       if (mat < 2) {
;         ss += __shfl_xor(ss, 1); ss += __shfl_xor(ss, 2); ss += __shfl_xor(ss, 4);
	s_waitcnt lgkmcnt(0)
	v_pk_fma_f32 v[18:19], v[18:19], v[82:83], v[56:57]
	v_div_fixup_f32 v14, v55, v54, v14
	v_mul_f32_e32 v16, 0xbfb8aa3b, v18
	v_exp_f32_e32 v56, v16
	v_mul_f32_e32 v16, 0xbfb8aa3b, v19
	v_exp_f32_e32 v57, v16
	v_pk_mul_f32 v[54:55], v[14:15], v[14:15]
	v_pk_add_f32 v[56:57], v[56:57], 1.0 op_sel_hi:[1,0]
	s_nop 0
	v_div_scale_f32 v16, s[38:39], v57, v57, v19
	v_rcp_f32_e32 v60, v16
	s_nop 0
	v_fma_f32 v82, -v16, v60, 1.0
	v_fmac_f32_e32 v60, v82, v60
	v_div_scale_f32 v82, vcc, v19, v57, v19
	v_mul_f32_e32 v83, v82, v60
	v_fma_f32 v84, -v16, v83, v82
	v_fmac_f32_e32 v83, v84, v60
	v_fma_f32 v16, -v16, v83, v82
	v_div_fmas_f32 v16, v16, v60, v83
	v_div_fixup_f32 v19, v16, v57, v19
	v_div_scale_f32 v16, s[38:39], v56, v56, v18
	v_rcp_f32_e32 v57, v16
	s_nop 0
	v_fma_f32 v60, -v16, v57, 1.0
	v_fmac_f32_e32 v57, v60, v57
	v_div_scale_f32 v60, vcc, v18, v56, v18
	v_mul_f32_e32 v82, v60, v57
	v_fma_f32 v83, -v16, v82, v60
	v_fmac_f32_e32 v82, v83, v57
	v_fma_f32 v16, -v16, v82, v60
	v_div_fmas_f32 v16, v16, v57, v82
	v_div_fixup_f32 v18, v16, v56, v18
	v_lshlrev_b32_e32 v16, 16, v17
	v_and_b32_e32 v17, 0xffff0000, v17
	v_pk_fma_f32 v[16:17], v[20:21], v[16:17], v[50:51]
	v_pk_mul_f32 v[56:57], v[18:19], v[18:19]
	v_mul_f32_e32 v20, 0xbfb8aa3b, v16
	v_mul_f32_e32 v21, 0xbfb8aa3b, v17
	v_exp_f32_e32 v20, v20
	v_exp_f32_e32 v21, v21
	s_nop 0
	v_pk_add_f32 v[20:21], v[20:21], 1.0 op_sel_hi:[1,0]
	s_nop 0
	v_div_scale_f32 v50, s[38:39], v21, v21, v17
	v_rcp_f32_e32 v51, v50
	s_nop 0
	v_fma_f32 v60, -v50, v51, 1.0
	v_fmac_f32_e32 v51, v60, v51
	v_div_scale_f32 v60, vcc, v17, v21, v17
	v_mul_f32_e32 v82, v60, v51
	v_fma_f32 v83, -v50, v82, v60
	v_fmac_f32_e32 v82, v83, v51
	v_fma_f32 v50, -v50, v82, v60
	v_div_fmas_f32 v50, v50, v51, v82
	v_div_fixup_f32 v17, v50, v21, v17
	v_div_scale_f32 v21, s[38:39], v20, v20, v16
	v_rcp_f32_e32 v50, v21
	s_nop 0
	v_fma_f32 v51, -v21, v50, 1.0
	v_fmac_f32_e32 v50, v51, v50
	v_div_scale_f32 v51, vcc, v16, v20, v16
	v_mul_f32_e32 v60, v51, v50
	v_fma_f32 v82, -v21, v60, v51
	v_fmac_f32_e32 v60, v82, v50
	v_fma_f32 v21, -v21, v60, v51
	v_div_fmas_f32 v21, v21, v50, v60
	v_lshlrev_b32_e32 v50, 16, v2
	v_and_b32_e32 v51, 0xffff0000, v2
	v_pk_fma_f32 v[10:11], v[10:11], v[50:51], v[48:49]
	v_div_fixup_f32 v16, v21, v20, v16
	v_mul_f32_e32 v2, 0xbfb8aa3b, v10
	v_exp_f32_e32 v48, v2
	v_mul_f32_e32 v2, 0xbfb8aa3b, v11
	v_exp_f32_e32 v49, v2
	v_pk_mul_f32 v[20:21], v[16:17], v[16:17]
	v_pk_add_f32 v[48:49], v[48:49], 1.0 op_sel_hi:[1,0]
	s_nop 0
	v_div_scale_f32 v2, s[38:39], v49, v49, v11
	v_rcp_f32_e32 v50, v2
	s_nop 0
	v_fma_f32 v51, -v2, v50, 1.0
	v_fmac_f32_e32 v50, v51, v50
	v_div_scale_f32 v51, vcc, v11, v49, v11
	v_mul_f32_e32 v60, v51, v50
	v_fma_f32 v82, -v2, v60, v51
	v_fmac_f32_e32 v60, v82, v50
	v_fma_f32 v2, -v2, v60, v51
	v_div_fmas_f32 v2, v2, v50, v60
	v_div_fixup_f32 v11, v2, v49, v11
	v_div_scale_f32 v2, s[38:39], v48, v48, v10
	v_rcp_f32_e32 v49, v2
	s_nop 0
	v_fma_f32 v50, -v2, v49, 1.0
	v_fmac_f32_e32 v49, v50, v49
	v_div_scale_f32 v50, vcc, v10, v48, v10
	v_mul_f32_e32 v51, v50, v49
	v_fma_f32 v60, -v2, v51, v50
	v_fmac_f32_e32 v51, v60, v49
	v_fma_f32 v2, -v2, v51, v50
	v_div_fmas_f32 v2, v2, v49, v51
	v_div_fixup_f32 v10, v2, v48, v10
	v_lshlrev_b32_e32 v2, 16, v3
	v_and_b32_e32 v3, 0xffff0000, v3
	v_pk_fma_f32 v[2:3], v[12:13], v[2:3], v[44:45]
	v_pk_mul_f32 v[48:49], v[10:11], v[10:11]
	v_mul_f32_e32 v12, 0xbfb8aa3b, v2
	v_mul_f32_e32 v13, 0xbfb8aa3b, v3
	v_exp_f32_e32 v12, v12
	v_exp_f32_e32 v13, v13
	s_nop 0
	v_pk_add_f32 v[12:13], v[12:13], 1.0 op_sel_hi:[1,0]
	s_nop 0
	v_div_scale_f32 v44, s[38:39], v13, v13, v3
	v_rcp_f32_e32 v45, v44
	s_nop 0
	v_fma_f32 v50, -v44, v45, 1.0
	v_fmac_f32_e32 v45, v50, v45
	v_div_scale_f32 v50, vcc, v3, v13, v3
	v_mul_f32_e32 v51, v50, v45
	v_fma_f32 v60, -v44, v51, v50
	v_fmac_f32_e32 v51, v60, v45
	v_fma_f32 v44, -v44, v51, v50
	v_div_fmas_f32 v44, v44, v45, v51
	v_div_fixup_f32 v3, v44, v13, v3
	v_div_scale_f32 v13, s[38:39], v12, v12, v2
	v_rcp_f32_e32 v44, v13
	s_nop 0
	v_fma_f32 v45, -v13, v44, 1.0
	v_fmac_f32_e32 v44, v45, v44
	v_div_scale_f32 v45, vcc, v2, v12, v2
	v_mul_f32_e32 v50, v45, v44
	v_fma_f32 v51, -v13, v50, v45
	v_fmac_f32_e32 v50, v51, v44
	v_fma_f32 v13, -v13, v50, v45
	v_div_fmas_f32 v13, v13, v44, v50
	v_lshlrev_b32_e32 v44, 16, v4
	v_and_b32_e32 v45, 0xffff0000, v4
	v_pk_fma_f32 v[6:7], v[6:7], v[44:45], v[42:43]
	v_div_fixup_f32 v2, v13, v12, v2
	v_mul_f32_e32 v4, 0xbfb8aa3b, v6
	v_exp_f32_e32 v42, v4
	v_mul_f32_e32 v4, 0xbfb8aa3b, v7
	v_exp_f32_e32 v43, v4
	v_pk_mul_f32 v[12:13], v[2:3], v[2:3]
	v_pk_add_f32 v[42:43], v[42:43], 1.0 op_sel_hi:[1,0]
	s_nop 0
	v_div_scale_f32 v4, s[38:39], v43, v43, v7
	v_rcp_f32_e32 v44, v4
	s_nop 0
	v_fma_f32 v45, -v4, v44, 1.0
	v_fmac_f32_e32 v44, v45, v44
	v_div_scale_f32 v45, vcc, v7, v43, v7
	v_mul_f32_e32 v50, v45, v44
	v_fma_f32 v51, -v4, v50, v45
	v_fmac_f32_e32 v50, v51, v44
	v_fma_f32 v4, -v4, v50, v45
	v_div_fmas_f32 v4, v4, v44, v50
	v_div_fixup_f32 v7, v4, v43, v7
	v_div_scale_f32 v4, s[38:39], v42, v42, v6
	v_rcp_f32_e32 v43, v4
	s_nop 0
	v_fma_f32 v44, -v4, v43, 1.0
	v_fmac_f32_e32 v43, v44, v43
	v_div_scale_f32 v44, vcc, v6, v42, v6
	v_mul_f32_e32 v45, v44, v43
	v_fma_f32 v50, -v4, v45, v44
	v_fmac_f32_e32 v45, v50, v43
	v_fma_f32 v4, -v4, v45, v44
	v_div_fmas_f32 v4, v4, v43, v45
	v_div_fixup_f32 v6, v4, v42, v6
	v_lshlrev_b32_e32 v4, 16, v5
	v_and_b32_e32 v5, 0xffff0000, v5
	v_pk_fma_f32 v[4:5], v[8:9], v[4:5], v[46:47]
	v_pk_mul_f32 v[42:43], v[6:7], v[6:7]
	v_mul_f32_e32 v8, 0xbfb8aa3b, v4
	v_mul_f32_e32 v9, 0xbfb8aa3b, v5
	v_exp_f32_e32 v8, v8
	v_exp_f32_e32 v9, v9
	s_nop 0
	v_pk_add_f32 v[8:9], v[8:9], 1.0 op_sel_hi:[1,0]
	s_nop 0
	v_div_scale_f32 v44, s[38:39], v9, v9, v5
	v_rcp_f32_e32 v45, v44
	s_nop 0
	v_fma_f32 v46, -v44, v45, 1.0
	v_fmac_f32_e32 v45, v46, v45
	v_div_scale_f32 v46, vcc, v5, v9, v5
	v_mul_f32_e32 v47, v46, v45
	v_fma_f32 v50, -v44, v47, v46
	v_fmac_f32_e32 v47, v50, v45
	v_fma_f32 v44, -v44, v47, v46
	v_div_fmas_f32 v44, v44, v45, v47
	v_div_fixup_f32 v5, v44, v9, v5
	v_div_scale_f32 v9, s[38:39], v8, v8, v4
	v_rcp_f32_e32 v44, v9
	s_nop 0
	v_fma_f32 v45, -v9, v44, 1.0
	v_fmac_f32_e32 v44, v45, v44
	v_div_scale_f32 v45, vcc, v4, v8, v4
	v_mul_f32_e32 v46, v45, v44
	v_fma_f32 v47, -v9, v46, v45
	v_fmac_f32_e32 v46, v47, v44
	v_fma_f32 v9, -v9, v46, v45
	v_div_fmas_f32 v9, v9, v44, v46
	v_add_f32_e32 v44, v52, v53
	v_add_f32_e32 v44, v54, v44
	v_add_f32_e32 v44, v55, v44
	v_add_f32_e32 v44, v56, v44
	v_add_f32_e32 v44, v57, v44
	v_add_f32_e32 v20, v20, v44
	v_add_f32_e32 v20, v21, v20
	v_add_f32_e32 v20, v20, v48
	v_add_f32_e32 v20, v49, v20
	v_add_f32_e32 v12, v12, v20
	v_add_f32_e32 v12, v13, v12
	v_div_fixup_f32 v4, v9, v8, v4
	v_add_f32_e32 v12, v42, v12
	v_pk_mul_f32 v[8:9], v[4:5], v[4:5]
	v_add_f32_e32 v12, v43, v12
	v_add_f32_e32 v8, v8, v12
	v_add_f32_e32 v8, v9, v8
	ds_bpermute_b32 v9, v185, v8
	v_mov_b32_e32 v12, 0
	v_mov_b32_e32 v13, 0
	v_mov_b32_e32 v99, v12
	v_mov_b32_e32 v96, v12
	s_waitcnt lgkmcnt(0)
; DI float bflo(u32 w) { return __uint_as_float(w << 16); }
; DI float bfhi(u32 w) { return __uint_as_float(w & 0xffff0000u); }
; DI void phase2(const P& p, char* smem, int bid, int nb) {
;     ...
;     for (int mat = 0; mat < 3; mat++) {
;       float val[16];
; #pragma unroll
;       for (int c = 0; c < 16; c++) val[c] = 0.f;
;       const int col = mat * 1024 + h * 128 + seg * 16;
; #pragma unroll
;       for (int j = 0; j < 4; j++) {
;         int tl = n * 64 + r - 3 + j;
;         if (tl >= 0) {
;           const u16* src = QKV + (size_t)(tok0 + r - 3 + j) * 3072 + col;
;           u32x4 r0 = *(const u32x4*)src, r1 = *(const u32x4*)(src + 8);
;           const float4* cw = (const float4*)(p.conv_w + j * 3072 + col);
;           float4 c0 = cw[0], c1 = cw[1], c2 = cw[2], c3 = cw[3];
;           val[0] += c0.x * bflo(r0[0]); val[1] += c0.y * bfhi(r0[0]); val[2] += c0.z * bflo(r0[1]); val[3] += c0.w * bfhi(r0[1]);
;           val[4] += c1.x * bflo(r0[2]); val[5] += c1.y * bfhi(r0[2]); val[6] += c1.z * bflo(r0[3]); val[7] += c1.w * bfhi(r0[3]);
;           val[8] += c2.x * bflo(r1[0]); val[9] += c2.y * bfhi(r1[0]); val[10] += c2.z * bflo(r1[1]); val[11] += c2.w * bfhi(r1[1]);
;           val[12] += c3.x * bflo(r1[2]); val[13] += c3.y * bfhi(r1[2]); val[14] += c3.z * bflo(r1[3]); val[15] += c3.w * bfhi(r1[3]);
;         }
;     ...
;       float ss = 0.f;
; #pragma unroll
;       for (int c = 0; c < 16; c++) { float x = val[c]; x = x / (1.f + __expf(-x)); val[c] = x; ss += x * x; }
;       if (mat < 2) {
;         ss += __shfl_xor(ss, 1); ss += __shfl_xor(ss, 2); ss += __shfl_xor(ss, 4);
;         float rinv = rsqrtf(ss + RMS_EPS) * (mat == 0 ? 0.08838834764831845f : 1.f);
; #pragma unroll
;         for (int c = 0; c < 16; c++) val[c] *= rinv;
;       }
; #pragma unroll
;       for (int c = 0; c < 16; c++) { if (mat == 0) qv[c] = val[c]; else if (mat == 1) kv[c] = val[c]; else vv[c] = val[c]; }
	v_add_f32_e32 v8, v8, v9
	ds_bpermute_b32 v9, v186, v8
	v_mov_b32_e32 v97, v12
	v_mov_b32_e32 v94, v12
	v_mov_b32_e32 v95, v12
	v_mov_b32_e32 v92, v12
	s_waitcnt lgkmcnt(0)
	v_add_f32_e32 v44, v8, v9
	ds_bpermute_b32 v45, v188, v44
	v_or_b32_e32 v8, 0x800, v77
	v_lshlrev_b32_e32 v60, 1, v8
	v_lshl_add_u64 v[20:21], s[16:17], 0, v[60:61]
	v_lshlrev_b32_e32 v60, 2, v8
	v_lshl_add_u64 v[8:9], s[30:31], 0, v[60:61]
	v_mov_b32_e32 v93, v12
	v_mov_b32_e32 v90, v12
	v_mov_b32_e32 v91, v12
	v_mov_b32_e32 v88, v12
	v_mov_b32_e32 v89, v12
	v_mov_b32_e32 v42, 0
	v_mov_b32_e32 v43, 0
	s_and_saveexec_b64 s[38:39], s[88:89]
	s_cbranch_execz .LBB0_150
	v_mad_i64_i32 v[12:13], s[40:41], v71, s46, v[20:21]
	global_load_dwordx4 v[46:49], v[12:13], off offset:16
	global_load_dwordx4 v[50:53], v[12:13], off
	v_subrev_u32_e32 v248, s100, v8
	v_lshrrev_b32_e32 v249, 12, v248
	v_and_b32_e32 v248, 0xfff, v248
	v_lshl_add_u32 v248, v249, 9, v248
	v_add_u32_e32 v248, 0x1e000, v248
	ds_read_b128 v[54:57], v248 offset:48
	v_subrev_u32_e32 v248, s100, v8
	v_lshrrev_b32_e32 v249, 12, v248
	v_and_b32_e32 v248, 0xfff, v248
	v_lshl_add_u32 v248, v249, 9, v248
	v_add_u32_e32 v248, 0x1e000, v248
	ds_read_b128 v[82:85], v248 offset:32
	v_subrev_u32_e32 v248, s100, v8
	v_lshrrev_b32_e32 v249, 12, v248
	v_and_b32_e32 v248, 0xfff, v248
	v_lshl_add_u32 v248, v249, 9, v248
	v_add_u32_e32 v248, 0x1e000, v248
	ds_read_b128 v[86:89], v248 offset:16
	v_subrev_u32_e32 v248, s100, v8
	v_lshrrev_b32_e32 v249, 12, v248
	v_and_b32_e32 v248, 0xfff, v248
	v_lshl_add_u32 v248, v249, 9, v248
	v_add_u32_e32 v248, 0x1e000, v248
	ds_read_b128 v[90:93], v248
	s_waitcnt vmcnt(0)
	s_waitcnt lgkmcnt(0)
	v_lshlrev_b32_e32 v12, 16, v50
	v_and_b32_e32 v13, 0xffff0000, v50
	s_waitcnt vmcnt(0)
	s_waitcnt lgkmcnt(0)
	v_pk_fma_f32 v[100:101], v[90:91], v[12:13], 0 op_sel_hi:[1,1,0]
	v_lshlrev_b32_e32 v12, 16, v51
	v_and_b32_e32 v13, 0xffff0000, v51
	v_pk_fma_f32 v[98:99], v[92:93], v[12:13], 0 op_sel_hi:[1,1,0]
	v_lshlrev_b32_e32 v12, 16, v52
	v_and_b32_e32 v13, 0xffff0000, v52
	v_pk_fma_f32 v[96:97], v[86:87], v[12:13], 0 op_sel_hi:[1,1,0]
	v_lshlrev_b32_e32 v12, 16, v53
	v_and_b32_e32 v13, 0xffff0000, v53
	v_pk_fma_f32 v[94:95], v[88:89], v[12:13], 0 op_sel_hi:[1,1,0]
	v_lshlrev_b32_e32 v12, 16, v46
	v_and_b32_e32 v13, 0xffff0000, v46
	v_pk_fma_f32 v[92:93], v[82:83], v[12:13], 0 op_sel_hi:[1,1,0]
	v_lshlrev_b32_e32 v12, 16, v47
	v_and_b32_e32 v13, 0xffff0000, v47
	v_pk_fma_f32 v[90:91], v[84:85], v[12:13], 0 op_sel_hi:[1,1,0]
	v_lshlrev_b32_e32 v12, 16, v48
	v_and_b32_e32 v13, 0xffff0000, v48
	v_pk_fma_f32 v[88:89], v[54:55], v[12:13], 0 op_sel_hi:[1,1,0]
	v_lshlrev_b32_e32 v12, 16, v49
	v_and_b32_e32 v13, 0xffff0000, v49
	v_pk_fma_f32 v[12:13], v[56:57], v[12:13], 0 op_sel_hi:[1,1,0]
	s_nop 0
	v_mov_b32_e32 v42, v12
	v_mov_b32_e32 v43, v13
	s_or_b64 exec, exec, s[38:39]
	s_and_saveexec_b64 s[38:39], s[90:91]
	s_cbranch_execnz .LBB0_151

; DI float bflo(u32 w) { return __uint_as_float(w << 16); }
; DI float bfhi(u32 w) { return __uint_as_float(w & 0xffff0000u); }
; DI void phase2(const P& p, char* smem, int bid, int nb) {
;     ...
; #pragma unroll
;       for (int j = 0; j < 4; j++) {
;         int tl = n * 64 + r - 3 + j;
;         if (tl >= 0) {
;           const u16* src = QKV + (size_t)(tok0 + r - 3 + j) * 3072 + col;
;           u32x4 r0 = *(const u32x4*)src, r1 = *(const u32x4*)(src + 8);
;           const float4* cw = (const float4*)(p.conv_w + j * 3072 + col);
;           float4 c0 = cw[0], c1 = cw[1], c2 = cw[2], c3 = cw[3];
;           val[0] += c0.x * bflo(r0[0]); val[1] += c0.y * bfhi(r0[0]); val[2] += c0.z * bflo(r0[1]); val[3] += c0.w * bfhi(r0[1]);
;           val[4] += c1.x * bflo(r0[2]); val[5] += c1.y * bfhi(r0[2]); val[6] += c1.z * bflo(r0[3]); val[7] += c1.w * bfhi(r0[3]);
;           val[8] += c2.x * bflo(r1[0]); val[9] += c2.y * bfhi(r1[0]); val[10] += c2.z * bflo(r1[1]); val[11] += c2.w * bfhi(r1[1]);
;           val[12] += c3.x * bflo(r1[2]); val[13] += c3.y * bfhi(r1[2]); val[14] += c3.z * bflo(r1[3]); val[15] += c3.w * bfhi(r1[3]);
;         }
;       }
;       float ss = 0.f;
; #pragma unroll
;       for (int c = 0; c < 16; c++) { float x = val[c]; x = x / (1.f + __expf(-x)); val[c] = x; ss += x * x; }
;       if (mat < 2) {
;         ss += __shfl_xor(ss, 1); ss += __shfl_xor(ss, 2); ss += __shfl_xor(ss, 4);
;         float rinv = rsqrtf(ss + RMS_EPS) * (mat == 0 ? 0.08838834764831845f : 1.f);
; #pragma unroll
;         for (int c = 0; c < 16; c++) val[c] *= rinv;
.LBB0_141:
	v_mad_i64_i32 v[12:13], s[40:41], v75, s46, v[20:21]
	global_load_dwordx4 v[46:49], v[12:13], off offset:16
	global_load_dwordx4 v[50:53], v[12:13], off
	v_add_co_u32_e32 v54, vcc, 0x6000, v8
	v_lshl_add_u64 v[12:13], v[8:9], 0, s[10:11]
	s_nop 0
	v_addc_co_u32_e32 v55, vcc, 0, v9, vcc
	v_subrev_u32_e32 v248, s100, v54
	v_lshrrev_b32_e32 v249, 12, v248
	v_and_b32_e32 v248, 0xfff, v248
	v_lshl_add_u32 v248, v249, 9, v248
	v_add_u32_e32 v248, 0x1e000, v248
	ds_read_b128 v[54:57], v248
	s_nop 0
	v_subrev_u32_e32 v248, s100, v12
	v_lshrrev_b32_e32 v249, 12, v248
	v_and_b32_e32 v248, 0xfff, v248
	v_lshl_add_u32 v248, v249, 9, v248
	v_add_u32_e32 v248, 0x1e000, v248
	ds_read_b128 v[82:85], v248 offset:48
	v_subrev_u32_e32 v248, s100, v12
	v_lshrrev_b32_e32 v249, 12, v248
	v_and_b32_e32 v248, 0xfff, v248
	v_lshl_add_u32 v248, v249, 9, v248
	v_add_u32_e32 v248, 0x1e000, v248
	ds_read_b128 v[232:235], v248 offset:32
	v_subrev_u32_e32 v248, s100, v12
	v_lshrrev_b32_e32 v249, 12, v248
	v_and_b32_e32 v248, 0xfff, v248
	v_lshl_add_u32 v248, v249, 9, v248
	v_add_u32_e32 v248, 0x1e000, v248
	ds_read_b128 v[236:239], v248 offset:16
	s_waitcnt vmcnt(0)
	s_waitcnt lgkmcnt(0)
	v_lshlrev_b32_e32 v12, 16, v50
	v_and_b32_e32 v13, 0xffff0000, v50
	s_waitcnt vmcnt(0)
	s_waitcnt lgkmcnt(0)
	v_pk_fma_f32 v[100:101], v[54:55], v[12:13], v[100:101]
	v_lshlrev_b32_e32 v12, 16, v51
	v_and_b32_e32 v13, 0xffff0000, v51
	v_pk_fma_f32 v[98:99], v[56:57], v[12:13], v[98:99]
	v_lshlrev_b32_e32 v12, 16, v52
	v_and_b32_e32 v13, 0xffff0000, v52
	s_waitcnt vmcnt(0)
	s_waitcnt lgkmcnt(0)
	v_pk_fma_f32 v[96:97], v[236:237], v[12:13], v[96:97]
	v_lshlrev_b32_e32 v12, 16, v53
	v_and_b32_e32 v13, 0xffff0000, v53
	v_pk_fma_f32 v[94:95], v[238:239], v[12:13], v[94:95]
	v_lshlrev_b32_e32 v12, 16, v46
	v_and_b32_e32 v13, 0xffff0000, v46
	v_pk_fma_f32 v[92:93], v[232:233], v[12:13], v[92:93]
	v_lshlrev_b32_e32 v12, 16, v47
	v_and_b32_e32 v13, 0xffff0000, v47
	v_pk_fma_f32 v[90:91], v[234:235], v[12:13], v[90:91]
	v_lshlrev_b32_e32 v12, 16, v48
	v_and_b32_e32 v13, 0xffff0000, v48
	v_pk_fma_f32 v[88:89], v[82:83], v[12:13], v[88:89]
	v_lshlrev_b32_e32 v12, 16, v49
	v_and_b32_e32 v13, 0xffff0000, v49
	v_pk_fma_f32 v[42:43], v[84:85], v[12:13], v[42:43]
.LBB0_142:
	s_or_b64 exec, exec, s[38:39]
	s_waitcnt lgkmcnt(0)
	v_add_f32_e32 v12, v44, v45
	v_add_f32_e32 v12, 0x358637bd, v12
	v_cmp_gt_f32_e32 vcc, s48, v12
	v_mul_f32_e32 v13, 0x4b800000, v12
	s_ashr_i32 s37, s36, 31
	v_cndmask_b32_e32 v12, v12, v13, vcc
	v_rsq_f32_e32 v12, v12
	s_lshl_b64 s[90:91], s[36:37], 14
	v_mov_b32_e32 v71, v61
	v_mov_b32_e32 v73, v61
	v_mul_f32_e32 v13, 0x45800000, v12
	v_cndmask_b32_e32 v12, v12, v13, vcc
	v_pk_mul_f32 v[46:47], v[2:3], v[12:13] op_sel_hi:[1,0]
	v_add_f32_e32 v2, v79, v81
	v_add_f32_e32 v2, 0x358637bd, v2
	v_cmp_gt_f32_e32 vcc, s48, v2
	v_mul_f32_e32 v3, 0x4b800000, v2
	v_pk_mul_f32 v[48:49], v[10:11], v[12:13] op_sel_hi:[1,0]
	v_cndmask_b32_e32 v2, v2, v3, vcc
	v_rsq_f32_e32 v2, v2
	v_lshl_add_u64 v[10:11], v[8:9], 0, s[34:35]
	v_pk_mul_f32 v[56:57], v[40:41], v[12:13] op_sel_hi:[1,0]
	v_pk_mul_f32 v[54:55], v[14:15], v[12:13] op_sel_hi:[1,0]
	v_mul_f32_e32 v3, 0x45800000, v2
	v_cndmask_b32_e32 v2, v2, v3, vcc
	v_mul_f32_e32 v2, 0x3db504f3, v2
	v_pk_mul_f32 v[84:85], v[22:23], v[2:3] op_sel_hi:[1,0]
	v_pk_mul_f32 v[82:83], v[24:25], v[2:3] op_sel_hi:[1,0]
	v_pk_mul_f32 v[26:27], v[26:27], v[2:3] op_sel_hi:[1,0]
	v_pk_mul_f32 v[24:25], v[28:29], v[2:3] op_sel_hi:[1,0]
	v_pk_mul_f32 v[86:87], v[30:31], v[2:3] op_sel_hi:[1,0]
	v_pk_mul_f32 v[30:31], v[32:33], v[2:3] op_sel_hi:[1,0]
	v_pk_mul_f32 v[28:29], v[34:35], v[2:3] op_sel_hi:[1,0]
	v_pk_mul_f32 v[22:23], v[36:37], v[2:3] op_sel_hi:[1,0]
	v_add_co_u32_e32 v2, vcc, s47, v8
	v_lshl_add_u64 v[32:33], v[20:21], 0, v[38:39]
	s_nop 0
	v_addc_co_u32_e32 v3, vcc, 0, v9, vcc
	v_pk_mul_f32 v[52:53], v[18:19], v[12:13] op_sel_hi:[1,0]
	v_pk_mul_f32 v[50:51], v[16:17], v[12:13] op_sel_hi:[1,0]
	v_pk_mul_f32 v[44:45], v[6:7], v[12:13] op_sel_hi:[1,0]
	v_pk_mul_f32 v[40:41], v[4:5], v[12:13] op_sel_hi:[1,0]
	v_subrev_u32_e32 v248, s100, v2
	v_lshrrev_b32_e32 v249, 12, v248
	v_and_b32_e32 v248, 0xfff, v248
	v_lshl_add_u32 v248, v249, 9, v248
	v_add_u32_e32 v248, 0x1e000, v248
	ds_read_b128 v[14:17], v248
	s_nop 0
	v_subrev_u32_e32 v248, s100, v10
	v_lshrrev_b32_e32 v249, 12, v248
	v_and_b32_e32 v248, 0xfff, v248
	v_lshl_add_u32 v248, v249, 9, v248
	v_add_u32_e32 v248, 0x1e000, v248
	ds_read_b128 v[2:5], v248 offset:48
	v_subrev_u32_e32 v248, s100, v10
	v_lshrrev_b32_e32 v249, 12, v248
	v_and_b32_e32 v248, 0xfff, v248
	v_lshl_add_u32 v248, v249, 9, v248
	v_add_u32_e32 v248, 0x1e000, v248
	ds_read_b128 v[6:9], v248 offset:32
	s_nop 0
	v_subrev_u32_e32 v248, s100, v10
	v_lshrrev_b32_e32 v249, 12, v248
	v_and_b32_e32 v248, 0xfff, v248
	v_lshl_add_u32 v248, v249, 9, v248
	v_add_u32_e32 v248, 0x1e000, v248
	ds_read_b128 v[10:13], v248 offset:16
	s_nop 0
	global_load_dwordx4 v[18:21], v[32:33], off offset:16
	s_nop 0
	global_load_dwordx4 v[32:35], v[32:33], off
	s_barrier
; DI float bflo(u32 w) { return __uint_as_float(w << 16); }
; DI float bfhi(u32 w) { return __uint_as_float(w & 0xffff0000u); }
; DI void phase2(const P& p, char* smem, int bid, int nb) {
;     ...
;           val[0] += c0.x * bflo(r0[0]); val[1] += c0.y * bfhi(r0[0]); val[2] += c0.z * bflo(r0[1]); val[3] += c0.w * bfhi(r0[1]);
;           val[4] += c1.x * bflo(r0[2]); val[5] += c1.y * bfhi(r0[2]); val[6] += c1.z * bflo(r0[3]); val[7] += c1.w * bfhi(r0[3]);
;           val[8] += c2.x * bflo(r1[0]); val[9] += c2.y * bfhi(r1[0]); val[10] += c2.z * bflo(r1[1]); val[11] += c2.w * bfhi(r1[1]);
;           val[12] += c3.x * bflo(r1[2]); val[13] += c3.y * bfhi(r1[2]); val[14] += c3.z * bflo(r1[3]); val[15] += c3.w * bfhi(r1[3]);
;         }
;       }
;       float ss = 0.f;
; #pragma unroll
;       for (int c = 0; c < 16; c++) { float x = val[c]; x = x / (1.f + __expf(-x)); val[c] = x; ss += x * x; }
	v_cvt_pk_bf16_f32 v39, v50, v51
	s_mov_b32 s92, 0
	s_waitcnt vmcnt(0)
	s_waitcnt lgkmcnt(0)
	v_lshlrev_b32_e32 v36, 16, v32
	v_fma_f32 v36, v14, v36, v100
	v_and_b32_e32 v14, 0xffff0000, v32
	v_fma_f32 v32, v15, v14, v101
	v_lshlrev_b32_e32 v14, 16, v33
	v_fma_f32 v37, v16, v14, v98
	v_and_b32_e32 v14, 0xffff0000, v33
	v_fma_f32 v33, v17, v14, v99
	v_lshlrev_b32_e32 v14, 16, v34
	v_fma_f32 v38, v10, v14, v96
	v_and_b32_e32 v10, 0xffff0000, v34
	v_fma_f32 v11, v11, v10, v97
	v_lshlrev_b32_e32 v10, 16, v35
	v_fma_f32 v17, v12, v10, v94
	v_and_b32_e32 v10, 0xffff0000, v35
	v_fma_f32 v15, v13, v10, v95
	v_lshlrev_b32_e32 v10, 16, v18
	v_fma_f32 v16, v6, v10, v92
	v_and_b32_e32 v6, 0xffff0000, v18
	v_fma_f32 v14, v7, v6, v93
	v_lshlrev_b32_e32 v6, 16, v19
	v_fma_f32 v12, v8, v6, v90
	v_and_b32_e32 v6, 0xffff0000, v19
	v_fma_f32 v10, v9, v6, v91
	v_lshlrev_b32_e32 v6, 16, v20
	v_fma_f32 v7, v2, v6, v88
	v_and_b32_e32 v2, 0xffff0000, v20
	v_fma_f32 v6, v3, v2, v89
	v_lshlrev_b32_e32 v2, 16, v21
	v_fma_f32 v3, v4, v2, v42
	v_and_b32_e32 v2, 0xffff0000, v21
	v_fmac_f32_e32 v43, v5, v2
	v_mul_f32_e32 v2, 0xbfb8aa3b, v36
	v_exp_f32_e32 v2, v2
	v_cvt_pk_bf16_f32 v92, v86, v87
	v_cvt_pk_bf16_f32 v95, v22, v23
	v_cvt_pk_bf16_f32 v93, v30, v31
	v_add_f32_e32 v2, 1.0, v2
	v_div_scale_f32 v4, s[38:39], v2, v2, v36
	v_rcp_f32_e32 v5, v4
	v_cvt_pk_bf16_f32 v88, v48, v49
	v_cvt_pk_bf16_f32 v89, v46, v47
	v_cvt_pk_bf16_f32 v90, v44, v45
	v_fma_f32 v8, -v4, v5, 1.0
	v_fmac_f32_e32 v5, v8, v5
	v_div_scale_f32 v8, vcc, v36, v2, v36
	v_mul_f32_e32 v9, v8, v5
	v_fma_f32 v13, -v4, v9, v8
	v_fmac_f32_e32 v9, v13, v5
	v_fma_f32 v4, -v4, v9, v8
	v_div_fmas_f32 v4, v4, v5, v9
	v_div_fixup_f32 v2, v4, v2, v36
	v_mul_f32_e32 v4, 0xbfb8aa3b, v32
	v_exp_f32_e32 v4, v4
	v_cvt_pk_bf16_f32 v36, v56, v57
	v_cvt_pk_bf16_f32 v94, v28, v29
	v_cvt_pk_bf16_f32 v91, v40, v41
	v_add_f32_e32 v4, 1.0, v4
	v_div_scale_f32 v5, s[38:39], v4, v4, v32
	v_rcp_f32_e32 v8, v5
	s_nop 0
	v_fma_f32 v9, -v5, v8, 1.0
	v_fmac_f32_e32 v8, v9, v8
	v_div_scale_f32 v9, vcc, v32, v4, v32
	v_mul_f32_e32 v13, v9, v8
	v_fma_f32 v18, -v5, v13, v9
	v_fmac_f32_e32 v13, v18, v8
	v_fma_f32 v5, -v5, v13, v9
	v_div_fmas_f32 v5, v5, v8, v13
	v_div_fixup_f32 v4, v5, v4, v32
	v_mul_f32_e32 v5, 0xbfb8aa3b, v37
	v_exp_f32_e32 v5, v5
	s_nop 0
	v_add_f32_e32 v5, 1.0, v5
	v_div_scale_f32 v8, s[38:39], v5, v5, v37
	v_rcp_f32_e32 v9, v8
	s_nop 0
	v_fma_f32 v13, -v8, v9, 1.0
	v_fmac_f32_e32 v9, v13, v9
	v_div_scale_f32 v13, vcc, v37, v5, v37
	v_mul_f32_e32 v18, v13, v9
	v_fma_f32 v19, -v8, v18, v13
	v_fmac_f32_e32 v18, v19, v9
	v_fma_f32 v8, -v8, v18, v13
	v_div_fmas_f32 v8, v8, v9, v18
	v_div_fixup_f32 v5, v8, v5, v37
	v_mul_f32_e32 v8, 0xbfb8aa3b, v33
	v_exp_f32_e32 v8, v8
	v_cvt_pk_bf16_f32 v37, v54, v55
	v_add_f32_e32 v8, 1.0, v8
	v_div_scale_f32 v9, s[38:39], v8, v8, v33
	v_rcp_f32_e32 v13, v9
	s_nop 0
	v_fma_f32 v18, -v9, v13, 1.0
	v_fmac_f32_e32 v13, v18, v13
	v_div_scale_f32 v18, vcc, v33, v8, v33
	v_mul_f32_e32 v19, v18, v13
	v_fma_f32 v20, -v9, v19, v18
	v_fmac_f32_e32 v19, v20, v13
	v_fma_f32 v9, -v9, v19, v18
	v_div_fmas_f32 v9, v9, v13, v19
	v_div_fixup_f32 v8, v9, v8, v33
	v_mul_f32_e32 v9, 0xbfb8aa3b, v38
	v_exp_f32_e32 v9, v9
	s_nop 0
	v_add_f32_e32 v9, 1.0, v9
	v_div_scale_f32 v13, s[38:39], v9, v9, v38
	v_rcp_f32_e32 v18, v13
	s_nop 0
	v_fma_f32 v19, -v13, v18, 1.0
	v_fmac_f32_e32 v18, v19, v18
	v_div_scale_f32 v19, vcc, v38, v9, v38
	v_mul_f32_e32 v20, v19, v18
	v_fma_f32 v21, -v13, v20, v19
	v_fmac_f32_e32 v20, v21, v18
	v_fma_f32 v13, -v13, v20, v19
	v_div_fmas_f32 v13, v13, v18, v20
	v_div_fixup_f32 v9, v13, v9, v38
	v_mul_f32_e32 v13, 0xbfb8aa3b, v11
	v_exp_f32_e32 v13, v13
	v_cvt_pk_bf16_f32 v38, v52, v53
	v_add_f32_e32 v13, 1.0, v13
	v_div_scale_f32 v18, s[38:39], v13, v13, v11
	v_rcp_f32_e32 v19, v18
	s_nop 0
	v_fma_f32 v20, -v18, v19, 1.0
	v_fmac_f32_e32 v19, v20, v19
	v_div_scale_f32 v20, vcc, v11, v13, v11
	v_mul_f32_e32 v21, v20, v19
	v_fma_f32 v32, -v18, v21, v20
	v_fmac_f32_e32 v21, v32, v19
	v_fma_f32 v18, -v18, v21, v20
	v_div_fmas_f32 v18, v18, v19, v21
	v_div_fixup_f32 v11, v18, v13, v11
	v_mul_f32_e32 v13, 0xbfb8aa3b, v17
	v_exp_f32_e32 v13, v13
	s_nop 0
	v_add_f32_e32 v13, 1.0, v13
	v_div_scale_f32 v18, s[38:39], v13, v13, v17
	v_rcp_f32_e32 v19, v18
	s_nop 0
	v_fma_f32 v20, -v18, v19, 1.0
	v_fmac_f32_e32 v19, v20, v19
	v_div_scale_f32 v20, vcc, v17, v13, v17
	v_mul_f32_e32 v21, v20, v19
	v_fma_f32 v32, -v18, v21, v20
	v_fmac_f32_e32 v21, v32, v19
	v_fma_f32 v18, -v18, v21, v20
	v_div_fmas_f32 v18, v18, v19, v21
	v_div_fixup_f32 v13, v18, v13, v17
	v_mul_f32_e32 v17, 0xbfb8aa3b, v15
	v_exp_f32_e32 v17, v17
	s_nop 0
	v_add_f32_e32 v17, 1.0, v17
	v_div_scale_f32 v18, s[38:39], v17, v17, v15
	v_rcp_f32_e32 v19, v18
	s_nop 0
	v_fma_f32 v20, -v18, v19, 1.0
	v_fmac_f32_e32 v19, v20, v19
	v_div_scale_f32 v20, vcc, v15, v17, v15
	v_mul_f32_e32 v21, v20, v19
	v_fma_f32 v32, -v18, v21, v20
	v_fmac_f32_e32 v21, v32, v19
	v_fma_f32 v18, -v18, v21, v20
	v_div_fmas_f32 v18, v18, v19, v21
	v_div_fixup_f32 v15, v18, v17, v15
	v_mul_f32_e32 v17, 0xbfb8aa3b, v16
	v_exp_f32_e32 v17, v17
	s_nop 0
	v_add_f32_e32 v17, 1.0, v17
	v_div_scale_f32 v18, s[38:39], v17, v17, v16
	v_rcp_f32_e32 v19, v18
	s_nop 0
	v_fma_f32 v20, -v18, v19, 1.0
	v_fmac_f32_e32 v19, v20, v19
	v_div_scale_f32 v20, vcc, v16, v17, v16
	v_mul_f32_e32 v21, v20, v19
	v_fma_f32 v32, -v18, v21, v20
	v_fmac_f32_e32 v21, v32, v19
	v_fma_f32 v18, -v18, v21, v20
	v_div_fmas_f32 v18, v18, v19, v21
	v_div_fixup_f32 v16, v18, v17, v16
	v_mul_f32_e32 v17, 0xbfb8aa3b, v14
	v_exp_f32_e32 v17, v17
	s_nop 0
	v_add_f32_e32 v17, 1.0, v17
; DI void phase2(const P& p, char* smem, int bid, int nb) {
;     ...
;       for (int c = 0; c < 16; c++) { float x = val[c]; x = x / (1.f + __expf(-x)); val[c] = x; ss += x * x; }
;     ...
;     const float gr = gc[r], br = bt[r], glast = gc[63];
;     const float eg = __expf(gr), ekd = __expf(glast - gr);
	v_div_scale_f32 v18, s[38:39], v17, v17, v14
	v_rcp_f32_e32 v19, v18
	s_nop 0
	v_fma_f32 v20, -v18, v19, 1.0
	v_fmac_f32_e32 v19, v20, v19
	v_div_scale_f32 v20, vcc, v14, v17, v14
	v_mul_f32_e32 v21, v20, v19
	v_fma_f32 v32, -v18, v21, v20
	v_fmac_f32_e32 v21, v32, v19
	v_fma_f32 v18, -v18, v21, v20
	v_div_fmas_f32 v18, v18, v19, v21
	v_div_fixup_f32 v14, v18, v17, v14
	v_mul_f32_e32 v17, 0xbfb8aa3b, v12
	v_exp_f32_e32 v17, v17
	s_nop 0
	v_add_f32_e32 v17, 1.0, v17
	v_div_scale_f32 v18, s[38:39], v17, v17, v12
	v_rcp_f32_e32 v19, v18
	s_nop 0
	v_fma_f32 v20, -v18, v19, 1.0
	v_fmac_f32_e32 v19, v20, v19
	v_div_scale_f32 v20, vcc, v12, v17, v12
	v_mul_f32_e32 v21, v20, v19
	v_fma_f32 v32, -v18, v21, v20
	v_fmac_f32_e32 v21, v32, v19
	v_fma_f32 v18, -v18, v21, v20
	v_div_fmas_f32 v18, v18, v19, v21
	v_div_fixup_f32 v12, v18, v17, v12
	v_mul_f32_e32 v17, 0xbfb8aa3b, v10
	v_exp_f32_e32 v17, v17
	s_nop 0
	v_add_f32_e32 v17, 1.0, v17
	v_div_scale_f32 v18, s[38:39], v17, v17, v10
	v_rcp_f32_e32 v19, v18
	s_nop 0
	v_fma_f32 v20, -v18, v19, 1.0
	v_fmac_f32_e32 v19, v20, v19
	v_div_scale_f32 v20, vcc, v10, v17, v10
	v_mul_f32_e32 v21, v20, v19
	v_fma_f32 v32, -v18, v21, v20
	v_fmac_f32_e32 v21, v32, v19
	v_fma_f32 v18, -v18, v21, v20
	v_div_fmas_f32 v18, v18, v19, v21
	v_div_fixup_f32 v10, v18, v17, v10
	v_mul_f32_e32 v17, 0xbfb8aa3b, v7
	v_exp_f32_e32 v17, v17
	s_nop 0
	v_add_f32_e32 v17, 1.0, v17
	v_div_scale_f32 v18, s[38:39], v17, v17, v7
	v_rcp_f32_e32 v19, v18
	s_nop 0
	v_fma_f32 v20, -v18, v19, 1.0
	v_fmac_f32_e32 v19, v20, v19
	v_div_scale_f32 v20, vcc, v7, v17, v7
	v_mul_f32_e32 v21, v20, v19
	v_fma_f32 v32, -v18, v21, v20
	v_fmac_f32_e32 v21, v32, v19
	v_fma_f32 v18, -v18, v21, v20
	v_div_fmas_f32 v18, v18, v19, v21
	v_div_fixup_f32 v7, v18, v17, v7
	v_mul_f32_e32 v17, 0xbfb8aa3b, v6
	v_exp_f32_e32 v17, v17
	s_nop 0
	v_add_f32_e32 v17, 1.0, v17
	v_div_scale_f32 v18, s[38:39], v17, v17, v6
	v_rcp_f32_e32 v19, v18
	s_nop 0
	v_fma_f32 v20, -v18, v19, 1.0
	v_fmac_f32_e32 v19, v20, v19
	v_div_scale_f32 v20, vcc, v6, v17, v6
	v_mul_f32_e32 v21, v20, v19
	v_fma_f32 v32, -v18, v21, v20
	v_fmac_f32_e32 v21, v32, v19
	v_fma_f32 v18, -v18, v21, v20
	v_div_fmas_f32 v18, v18, v19, v21
	v_div_fixup_f32 v17, v18, v17, v6
	v_mul_f32_e32 v6, 0xbfb8aa3b, v3
	v_exp_f32_e32 v6, v6
	s_nop 0
	v_add_f32_e32 v6, 1.0, v6
	v_div_scale_f32 v18, s[38:39], v6, v6, v3
	v_rcp_f32_e32 v19, v18
	s_nop 0
	v_fma_f32 v20, -v18, v19, 1.0
	v_fmac_f32_e32 v19, v20, v19
	v_div_scale_f32 v20, vcc, v3, v6, v3
	v_mul_f32_e32 v21, v20, v19
	v_fma_f32 v32, -v18, v21, v20
	v_fmac_f32_e32 v21, v32, v19
	v_fma_f32 v18, -v18, v21, v20
	v_div_fmas_f32 v18, v18, v19, v21
	v_div_fixup_f32 v3, v18, v6, v3
	v_mul_f32_e32 v6, 0xbfb8aa3b, v43
	v_exp_f32_e32 v6, v6
	s_nop 0
	v_add_f32_e32 v6, 1.0, v6
	v_div_scale_f32 v18, s[38:39], v6, v6, v43
	v_rcp_f32_e32 v19, v18
	s_lshl_b64 s[38:39], s[36:37], 15
	s_add_u32 s88, s42, s38
	s_addc_u32 s89, s43, s39
	v_fma_f32 v20, -v18, v19, 1.0
	v_fmac_f32_e32 v19, v20, v19
	v_div_scale_f32 v20, vcc, v43, v6, v43
	v_mul_f32_e32 v21, v20, v19
	v_fma_f32 v32, -v18, v21, v20
	v_fmac_f32_e32 v21, v32, v19
	v_fma_f32 v18, -v18, v21, v20
	v_div_fmas_f32 v18, v18, v19, v21
	v_div_fixup_f32 v42, v18, v6, v43
	ds_read_b32 v18, v103
	ds_read_b32 v43, v104
	v_mov_b32_e32 v6, s49
	ds_read_b32 v19, v6
	s_mov_b64 s[38:39], 0x4000
	s_waitcnt lgkmcnt(0)
	v_mul_f32_e32 v6, 0x3fb8aa3b, v18
	v_exp_f32_e32 v6, v6
	s_waitcnt lgkmcnt(0)
	v_mul_f32_e32 v2, v2, v43
	s_waitcnt lgkmcnt(0)
; DI u32 pack2(float a, float b) { f32x2 v = {a, b}; bfx2 r = __builtin_convertvector(v, bfx2); return __builtin_bit_cast(u32, r); }
; DI u16 f2bf(float x) { return (u16)(pack2(x, x) & 0xffffu); }
; DI void phase2(const P& p, char* smem, int bid, int nb) {
;     ...
;     const float gr = gc[r], br = bt[r], glast = gc[63];
;     const float eg = __expf(gr), ekd = __expf(glast - gr);
;     u16* qg_out = KDQG + (size_t)sidx * 16384 + 8192;
;     u16* kdT_out = KDQG + (size_t)sidx * 16384;
;     {
;       u32x4 o0, o1, k0, k1, q0, q1;
; #pragma unroll
;       for (int c = 0; c < 4; c++) {
;         o0[c] = pack2(qv[2 * c] * eg, qv[2 * c + 1] * eg); o1[c] = pack2(qv[8 + 2 * c] * eg, qv[9 + 2 * c] * eg);
;         k0[c] = pack2(kv[2 * c], kv[2 * c + 1]); k1[c] = pack2(kv[8 + 2 * c], kv[9 + 2 * c]);
;         q0[c] = pack2(qv[2 * c], qv[2 * c + 1]); q1[c] = pack2(qv[8 + 2 * c], qv[9 + 2 * c]);
;       }
;       *(u32x4*)(qg_out + r * 128 + seg * 16) = o0; *(u32x4*)(qg_out + r * 128 + seg * 16 + 8) = o1;
;       *(u32x4*)(Kb + r * 136 + seg * 16) = k0; *(u32x4*)(Kb + r * 136 + seg * 16 + 8) = k1;
;       *(u32x4*)(Qb + r * 136 + seg * 16) = q0; *(u32x4*)(Qb + r * 136 + seg * 16 + 8) = q1;
;     }
;     {
;       const int ob = seg * 16 * 72 + (((r >> 3) ^ seg) << 3) + (r & 7);
;       const int og = seg * 16 * 64 + r;
;       const float sk = br * eg;
; #pragma unroll
;       for (int c = 0; c < 16; c++) {
;         kdT_out[og + c * 64] = f2bf(kv[c] * ekd);
;         KBGt[ob + c * 72] = f2bf(kv[c] * sk);
;         VBt[ob + c * 72] = f2bf(vv[c] * br);
;       }
	v_sub_f32_e32 v18, v19, v18
	v_mul_f32_e32 v60, 0x3fb8aa3b, v18
	v_pk_mul_f32 v[20:21], v[86:87], v[6:7] op_sel_hi:[1,0]
	v_pk_mul_f32 v[18:19], v[84:85], v[6:7] op_sel_hi:[1,0]
	v_cvt_pk_bf16_f32 v32, v20, v21
	v_pk_mul_f32 v[20:21], v[82:83], v[6:7] op_sel_hi:[1,0]
	v_cvt_pk_bf16_f32 v18, v18, v19
	v_cvt_pk_bf16_f32 v19, v20, v21
	v_pk_mul_f32 v[20:21], v[30:31], v[6:7] op_sel_hi:[1,0]
	v_cvt_pk_bf16_f32 v86, v26, v27
	v_cvt_pk_bf16_f32 v33, v20, v21
	v_pk_mul_f32 v[20:21], v[26:27], v[6:7] op_sel_hi:[1,0]
	v_pk_mul_f32 v[26:27], v[24:25], v[6:7] op_sel_hi:[1,0]
	v_cvt_pk_bf16_f32 v20, v20, v21
	v_cvt_pk_bf16_f32 v21, v26, v27
	v_pk_mul_f32 v[26:27], v[22:23], v[6:7] op_sel_hi:[1,0]
	v_lshl_add_u64 v[22:23], s[88:89], 0, v[70:71]
	v_cvt_pk_bf16_f32 v35, v26, v27
	v_exp_f32_e32 v26, v60
	v_lshl_add_u64 v[22:23], v[22:23], 0, v[72:73]
	v_cvt_pk_bf16_f32 v87, v24, v25
	v_lshl_add_u64 v[24:25], v[22:23], 0, s[38:39]
	s_movk_i32 s38, 0x4000
	v_add_co_u32_e32 v22, vcc, s38, v22
	v_pk_mul_f32 v[30:31], v[28:29], v[6:7] op_sel_hi:[1,0]
	s_nop 0
	v_addc_co_u32_e32 v23, vcc, 0, v23, vcc
	v_cvt_pk_bf16_f32 v2, v2, s0
	v_cvt_pk_bf16_f32 v84, v84, v85
	v_cvt_pk_bf16_f32 v85, v82, v83
	v_cvt_pk_bf16_f32 v34, v30, v31
	global_store_dwordx4 v[22:23], v[18:21], off
	global_store_dwordx4 v[24:25], v[32:35], off offset:16
	ds_write_b128 v105, v[36:39]
	ds_write_b128 v105, v[88:91] offset:16
	ds_write_b128 v105, v[84:87] offset:17408
	ds_write_b128 v105, v[92:95] offset:17424
	ds_write_b16 v113, v2
	v_mul_f32_e32 v2, v57, v26
	v_mul_f32_e32 v6, v43, v6
	v_cvt_pk_bf16_f32 v2, v2, s0
	global_store_short v207, v2, s[88:89] offset:128
	v_mul_f32_e32 v2, v57, v6
	v_cvt_pk_bf16_f32 v2, v2, s0
	ds_write_b16 v114, v2
	v_mul_f32_e32 v2, v4, v43
	v_cvt_pk_bf16_f32 v2, v2, s0
	ds_write_b16 v115, v2
	v_mul_f32_e32 v2, v54, v26
	v_cvt_pk_bf16_f32 v2, v2, s0
	global_store_short v207, v2, s[88:89] offset:256
	v_mul_f32_e32 v2, v54, v6
	v_cvt_pk_bf16_f32 v2, v2, s0
	ds_write_b16 v116, v2
	v_mul_f32_e32 v2, v5, v43
	v_cvt_pk_bf16_f32 v2, v2, s0
	ds_write_b16 v117, v2
	v_mul_f32_e32 v2, v55, v26
	v_cvt_pk_bf16_f32 v2, v2, s0
	global_store_short v207, v2, s[88:89] offset:384
	v_mul_f32_e32 v2, v55, v6
	v_cvt_pk_bf16_f32 v2, v2, s0
	ds_write_b16 v118, v2
	v_mul_f32_e32 v2, v8, v43
	v_cvt_pk_bf16_f32 v2, v2, s0
	ds_write_b16 v119, v2
	v_mul_f32_e32 v2, v52, v26
	v_cvt_pk_bf16_f32 v2, v2, s0
	global_store_short v207, v2, s[88:89] offset:512
	v_mul_f32_e32 v2, v52, v6
	v_cvt_pk_bf16_f32 v2, v2, s0
	ds_write_b16 v120, v2
	v_mul_f32_e32 v2, v9, v43
	v_cvt_pk_bf16_f32 v2, v2, s0
	ds_write_b16 v121, v2
	v_mul_f32_e32 v2, v53, v26
	v_cvt_pk_bf16_f32 v2, v2, s0
	global_store_short v207, v2, s[88:89] offset:640
	v_mul_f32_e32 v2, v53, v6
	v_cvt_pk_bf16_f32 v2, v2, s0
	ds_write_b16 v122, v2
	v_mul_f32_e32 v2, v11, v43
	v_cvt_pk_bf16_f32 v2, v2, s0
	ds_write_b16 v123, v2
	v_mul_f32_e32 v2, v50, v26
	v_cvt_pk_bf16_f32 v2, v2, s0
	global_store_short v207, v2, s[88:89] offset:768
	v_mul_f32_e32 v2, v50, v6
	v_cvt_pk_bf16_f32 v2, v2, s0
	ds_write_b16 v124, v2
	v_mul_f32_e32 v2, v13, v43
	v_cvt_pk_bf16_f32 v2, v2, s0
	ds_write_b16 v125, v2
	v_mul_f32_e32 v2, v51, v26
	v_cvt_pk_bf16_f32 v2, v2, s0
	global_store_short v207, v2, s[88:89] offset:896
	v_mul_f32_e32 v2, v51, v6
	v_cvt_pk_bf16_f32 v2, v2, s0
	ds_write_b16 v126, v2
	v_mul_f32_e32 v2, v15, v43
	v_cvt_pk_bf16_f32 v2, v2, s0
	ds_write_b16 v127, v2
	v_mul_f32_e32 v2, v48, v26
	v_cvt_pk_bf16_f32 v2, v2, s0
	global_store_short v207, v2, s[88:89] offset:1024
	v_mul_f32_e32 v2, v48, v6
	v_cvt_pk_bf16_f32 v2, v2, s0
	ds_write_b16 v128, v2
	v_mul_f32_e32 v2, v16, v43
	v_cvt_pk_bf16_f32 v2, v2, s0
	ds_write_b16 v129, v2
	v_mul_f32_e32 v2, v49, v26
	v_cvt_pk_bf16_f32 v2, v2, s0
	global_store_short v207, v2, s[88:89] offset:1152
	v_mul_f32_e32 v2, v49, v6
	v_cvt_pk_bf16_f32 v2, v2, s0
	ds_write_b16 v130, v2
	v_mul_f32_e32 v2, v14, v43
	v_cvt_pk_bf16_f32 v2, v2, s0
	ds_write_b16 v131, v2
	v_mul_f32_e32 v2, v46, v26
	v_cvt_pk_bf16_f32 v2, v2, s0
	global_store_short v207, v2, s[88:89] offset:1280
	v_mul_f32_e32 v2, v46, v6
	v_cvt_pk_bf16_f32 v2, v2, s0
	ds_write_b16 v132, v2
	v_mul_f32_e32 v2, v12, v43
	v_cvt_pk_bf16_f32 v2, v2, s0
	ds_write_b16 v133, v2
	v_mul_f32_e32 v2, v47, v26
	v_cvt_pk_bf16_f32 v2, v2, s0
	global_store_short v207, v2, s[88:89] offset:1408
	v_mul_f32_e32 v2, v47, v6
	v_cvt_pk_bf16_f32 v2, v2, s0
	ds_write_b16 v134, v2
	v_mul_f32_e32 v2, v10, v43
	v_cvt_pk_bf16_f32 v2, v2, s0
	ds_write_b16 v135, v2
	v_mul_f32_e32 v2, v44, v26
	v_cvt_pk_bf16_f32 v2, v2, s0
	global_store_short v207, v2, s[88:89] offset:1536
	v_mul_f32_e32 v2, v44, v6
	v_cvt_pk_bf16_f32 v2, v2, s0
	ds_write_b16 v136, v2
	v_mul_f32_e32 v2, v7, v43
	v_cvt_pk_bf16_f32 v2, v2, s0
	ds_write_b16 v137, v2
	v_mul_f32_e32 v2, v45, v26
	v_cvt_pk_bf16_f32 v2, v2, s0
	global_store_short v207, v2, s[88:89] offset:1664
	v_mul_f32_e32 v2, v45, v6
	v_cvt_pk_bf16_f32 v2, v2, s0
	ds_write_b16 v138, v2
	v_mul_f32_e32 v2, v43, v17
	v_cvt_pk_bf16_f32 v2, v2, s0
	ds_write_b16 v139, v2
	v_mul_f32_e32 v2, v40, v26
	v_cvt_pk_bf16_f32 v2, v2, s0
	global_store_short v207, v2, s[88:89] offset:1792
	v_mul_f32_e32 v2, v40, v6
	v_cvt_pk_bf16_f32 v2, v2, s0
	ds_write_b16 v140, v2
	v_mul_f32_e32 v2, v43, v3
	v_cvt_pk_bf16_f32 v2, v2, s0
	ds_write_b16 v141, v2
	v_mul_f32_e32 v2, v41, v26
	v_cvt_pk_bf16_f32 v2, v2, s0
	global_store_short v207, v2, s[88:89] offset:1920
	v_mul_f32_e32 v2, v41, v6
	v_mul_f32_e32 v18, v56, v26
	v_cvt_pk_bf16_f32 v2, v2, s0
	v_cvt_pk_bf16_f32 v18, v18, s0
	ds_write_b16 v142, v2
	v_mul_f32_e32 v2, v43, v42
	global_store_short v207, v18, s[88:89]
	v_mul_f32_e32 v18, v56, v6
	v_cvt_pk_bf16_f32 v2, v2, s0
	v_cvt_pk_bf16_f32 v18, v18, s0
	ds_write_b16 v143, v2
	s_mov_b64 s[38:39], 0
	v_mov_b32_e32 v2, v206
	ds_write_b16 v112, v18
	s_branch .LBB0_144

; DI float bflo(u32 w) { return __uint_as_float(w << 16); }
; DI float bfhi(u32 w) { return __uint_as_float(w & 0xffff0000u); }
; DI void phase2(const P& p, char* smem, int bid, int nb) {
;     ...
;         int tl = n * 64 + r - 3 + j;
;         if (tl >= 0) {
;           const u16* src = QKV + (size_t)(tok0 + r - 3 + j) * 3072 + col;
;           u32x4 r0 = *(const u32x4*)src, r1 = *(const u32x4*)(src + 8);
;           const float4* cw = (const float4*)(p.conv_w + j * 3072 + col);
;           float4 c0 = cw[0], c1 = cw[1], c2 = cw[2], c3 = cw[3];
;           val[0] += c0.x * bflo(r0[0]); val[1] += c0.y * bfhi(r0[0]); val[2] += c0.z * bflo(r0[1]); val[3] += c0.w * bfhi(r0[1]);
;           val[4] += c1.x * bflo(r0[2]); val[5] += c1.y * bfhi(r0[2]); val[6] += c1.z * bflo(r0[3]); val[7] += c1.w * bfhi(r0[3]);
;           val[8] += c2.x * bflo(r1[0]); val[9] += c2.y * bfhi(r1[0]); val[10] += c2.z * bflo(r1[1]); val[11] += c2.w * bfhi(r1[1]);
;           val[12] += c3.x * bflo(r1[2]); val[13] += c3.y * bfhi(r1[2]); val[14] += c3.z * bflo(r1[3]); val[15] += c3.w * bfhi(r1[3]);
.LBB0_149:
	v_mov_b64_e32 v[4:5], s[16:17]
	v_mad_i64_i32 v[4:5], s[40:41], v73, s46, v[4:5]
	v_lshl_add_u64 v[4:5], v[4:5], 0, v[60:61]
	global_load_dwordx4 v[8:11], v[4:5], off offset:16
	global_load_dwordx4 v[12:15], v[4:5], off
	s_movk_i32 s37, 0x3000
	v_add_co_u32_e32 v16, vcc, s37, v6
	v_lshl_add_u64 v[4:5], v[6:7], 0, s[28:29]
	s_nop 0
	v_addc_co_u32_e32 v17, vcc, 0, v7, vcc
	v_subrev_u32_e32 v248, s100, v16
	v_lshrrev_b32_e32 v249, 12, v248
	v_and_b32_e32 v248, 0xfff, v248
	v_lshl_add_u32 v248, v249, 9, v248
	v_add_u32_e32 v248, 0x1e000, v248
	ds_read_b128 v[16:19], v248
	s_nop 0
	v_subrev_u32_e32 v248, s100, v4
	v_lshrrev_b32_e32 v249, 12, v248
	v_and_b32_e32 v248, 0xfff, v248
	v_lshl_add_u32 v248, v249, 9, v248
	v_add_u32_e32 v248, 0x1e000, v248
	ds_read_b128 v[82:85], v248 offset:48
	v_subrev_u32_e32 v248, s100, v4
	v_lshrrev_b32_e32 v249, 12, v248
	v_and_b32_e32 v248, 0xfff, v248
	v_lshl_add_u32 v248, v249, 9, v248
	v_add_u32_e32 v248, 0x1e000, v248
	ds_read_b128 v[86:89], v248 offset:32
	v_subrev_u32_e32 v248, s100, v4
	v_lshrrev_b32_e32 v249, 12, v248
	v_and_b32_e32 v248, 0xfff, v248
	v_lshl_add_u32 v248, v249, 9, v248
	v_add_u32_e32 v248, 0x1e000, v248
	ds_read_b128 v[90:93], v248 offset:16
	s_waitcnt vmcnt(0)
	s_waitcnt lgkmcnt(0)
	v_lshlrev_b32_e32 v4, 16, v12
	v_and_b32_e32 v5, 0xffff0000, v12
	s_waitcnt vmcnt(0)
	s_waitcnt lgkmcnt(0)
	v_pk_fma_f32 v[40:41], v[16:17], v[4:5], v[40:41]
	v_lshlrev_b32_e32 v4, 16, v13
	v_and_b32_e32 v5, 0xffff0000, v13
	v_pk_fma_f32 v[54:55], v[18:19], v[4:5], v[54:55]
	v_lshlrev_b32_e32 v4, 16, v14
	v_and_b32_e32 v5, 0xffff0000, v14
	s_waitcnt vmcnt(0)
	s_waitcnt lgkmcnt(0)
	v_pk_fma_f32 v[56:57], v[90:91], v[4:5], v[56:57]
	v_lshlrev_b32_e32 v4, 16, v15
	v_and_b32_e32 v5, 0xffff0000, v15
	v_pk_fma_f32 v[50:51], v[92:93], v[4:5], v[50:51]
	v_lshlrev_b32_e32 v4, 16, v8
	v_and_b32_e32 v5, 0xffff0000, v8
	v_pk_fma_f32 v[48:49], v[86:87], v[4:5], v[48:49]
	v_lshlrev_b32_e32 v4, 16, v9
	v_and_b32_e32 v5, 0xffff0000, v9
	v_pk_fma_f32 v[44:45], v[88:89], v[4:5], v[44:45]
	v_lshlrev_b32_e32 v4, 16, v10
	v_and_b32_e32 v5, 0xffff0000, v10
	v_pk_fma_f32 v[42:43], v[82:83], v[4:5], v[42:43]
	v_lshlrev_b32_e32 v4, 16, v11
	v_and_b32_e32 v5, 0xffff0000, v11
	v_pk_fma_f32 v[46:47], v[84:85], v[4:5], v[2:3]
	s_or_b64 exec, exec, s[38:39]
	s_and_saveexec_b64 s[38:39], s[92:93]
	s_cbranch_execnz .LBB0_137
	s_branch .LBB0_138

; DI float bflo(u32 w) { return __uint_as_float(w << 16); }
; DI float bfhi(u32 w) { return __uint_as_float(w & 0xffff0000u); }
; DI f32x4 mfma16(bf16x8 a, bf16x8 b, f32x4 c) { return __builtin_amdgcn_mfma_f32_16x16x32_bf16(a, b, c, 0, 0, 0); }
; DI void phase2(const P& p, char* smem, int bid, int nb) {
;     ...
;         int tl = n * 64 + r - 3 + j;
;         if (tl >= 0) {
;           const u16* src = QKV + (size_t)(tok0 + r - 3 + j) * 3072 + col;
;           u32x4 r0 = *(const u32x4*)src, r1 = *(const u32x4*)(src + 8);
;           const float4* cw = (const float4*)(p.conv_w + j * 3072 + col);
;           float4 c0 = cw[0], c1 = cw[1], c2 = cw[2], c3 = cw[3];
;           val[0] += c0.x * bflo(r0[0]); val[1] += c0.y * bfhi(r0[0]); val[2] += c0.z * bflo(r0[1]); val[3] += c0.w * bfhi(r0[1]);
;           val[4] += c1.x * bflo(r0[2]); val[5] += c1.y * bfhi(r0[2]); val[6] += c1.z * bflo(r0[3]); val[7] += c1.w * bfhi(r0[3]);
;           val[8] += c2.x * bflo(r1[0]); val[9] += c2.y * bfhi(r1[0]); val[10] += c2.z * bflo(r1[1]); val[11] += c2.w * bfhi(r1[1]);
;           val[12] += c3.x * bflo(r1[2]); val[13] += c3.y * bfhi(r1[2]); val[14] += c3.z * bflo(r1[3]); val[15] += c3.w * bfhi(r1[3]);
;     ...
;       for (int kk = 0; kk < 4; kk++) {
;         bf16x8 bq = ldfrag(Qb + (ti * 16 + (lane & 15)) * 136 + kk * 32 + (lane >> 4) * 8);
; #pragma unroll
;         for (int tj = 0; tj < 4; tj++) {
;           bf16x8 ak = ldfrag(Kb + (tj * 16 + (lane & 15)) * 136 + kk * 32 + (lane >> 4) * 8);
;           c4[tj] = mfma16(ak, bq, c4[tj]);
;         }
;       }
;       const int i = ti * 16 + (lane & 15);
;       const float gi = gc[i];
;       u16* intra_out = INTRA + (size_t)sidx * 4096;
; #pragma unroll
;       for (int tj = 0; tj < 4; tj++) {
;         float o[4];
; #pragma unroll
;         for (int rr = 0; rr < 4; rr++) {
;           int j = tj * 16 + 4 * (lane >> 4) + rr;
;           o[rr] = (j <= i) ? c4[tj][rr] * __expf(gi - gc[j]) : 0.f;
.LBB0_151:
	v_mad_i64_i32 v[42:43], s[40:41], v73, s46, v[20:21]
	global_load_dwordx4 v[46:49], v[42:43], off offset:16
	global_load_dwordx4 v[50:53], v[42:43], off
	v_add_co_u32_e32 v54, vcc, 0x3000, v8
	v_lshl_add_u64 v[42:43], v[8:9], 0, s[28:29]
	s_nop 0
	v_addc_co_u32_e32 v55, vcc, 0, v9, vcc
	v_subrev_u32_e32 v248, s100, v54
	v_lshrrev_b32_e32 v249, 12, v248
	v_and_b32_e32 v248, 0xfff, v248
	v_lshl_add_u32 v248, v249, 9, v248
	v_add_u32_e32 v248, 0x1e000, v248
	ds_read_b128 v[54:57], v248
	s_nop 0
	v_subrev_u32_e32 v248, s100, v42
	v_lshrrev_b32_e32 v249, 12, v248
	v_and_b32_e32 v248, 0xfff, v248
	v_lshl_add_u32 v248, v249, 9, v248
	v_add_u32_e32 v248, 0x1e000, v248
	ds_read_b128 v[82:85], v248 offset:48
	v_subrev_u32_e32 v248, s100, v42
	v_lshrrev_b32_e32 v249, 12, v248
	v_and_b32_e32 v248, 0xfff, v248
	v_lshl_add_u32 v248, v249, 9, v248
	v_add_u32_e32 v248, 0x1e000, v248
	ds_read_b128 v[232:235], v248 offset:32
	v_subrev_u32_e32 v248, s100, v42
	v_lshrrev_b32_e32 v249, 12, v248
	v_and_b32_e32 v248, 0xfff, v248
	v_lshl_add_u32 v248, v249, 9, v248
	v_add_u32_e32 v248, 0x1e000, v248
	ds_read_b128 v[236:239], v248 offset:16
	s_waitcnt vmcnt(0)
	s_waitcnt lgkmcnt(0)
	v_lshlrev_b32_e32 v42, 16, v50
	v_and_b32_e32 v43, 0xffff0000, v50
	s_waitcnt vmcnt(0)
	s_waitcnt lgkmcnt(0)
	v_pk_fma_f32 v[100:101], v[54:55], v[42:43], v[100:101]
	v_lshlrev_b32_e32 v42, 16, v51
	v_and_b32_e32 v43, 0xffff0000, v51
	v_pk_fma_f32 v[98:99], v[56:57], v[42:43], v[98:99]
	v_lshlrev_b32_e32 v42, 16, v52
	v_and_b32_e32 v43, 0xffff0000, v52
	s_waitcnt vmcnt(0)
	s_waitcnt lgkmcnt(0)
	v_pk_fma_f32 v[96:97], v[236:237], v[42:43], v[96:97]
	v_lshlrev_b32_e32 v42, 16, v53
	v_and_b32_e32 v43, 0xffff0000, v53
	v_pk_fma_f32 v[94:95], v[238:239], v[42:43], v[94:95]
	v_lshlrev_b32_e32 v42, 16, v46
	v_and_b32_e32 v43, 0xffff0000, v46
	v_pk_fma_f32 v[92:93], v[232:233], v[42:43], v[92:93]
	v_lshlrev_b32_e32 v42, 16, v47
	v_and_b32_e32 v43, 0xffff0000, v47
	v_pk_fma_f32 v[90:91], v[234:235], v[42:43], v[90:91]
	v_lshlrev_b32_e32 v42, 16, v48
	v_and_b32_e32 v43, 0xffff0000, v48
	v_pk_fma_f32 v[88:89], v[82:83], v[42:43], v[88:89]
	v_lshlrev_b32_e32 v42, 16, v49
	v_and_b32_e32 v43, 0xffff0000, v49
	v_pk_fma_f32 v[42:43], v[84:85], v[42:43], v[12:13]
	s_or_b64 exec, exec, s[38:39]
	s_and_saveexec_b64 s[38:39], s[92:93]
	s_cbranch_execnz .LBB0_141
	s_branch .LBB0_142
.LBB0_152:
	s_or_b64 exec, exec, s[38:39]
	s_waitcnt lgkmcnt(0)
	s_barrier
	v_readlane_b32 s38, v251, 15
	v_readlane_b32 s39, v251, 16
	s_lshr_b32 vcc_lo, s33, 3
	s_lshl_b32 vcc_lo, vcc_lo, 6
	s_add_i32 vcc_lo, vcc_lo, 0x7fd
	s_mul_i32 vcc_lo, vcc_lo, 0x1800
	s_and_b32 vcc_hi, s33, 7
	s_lshl_b32 vcc_hi, vcc_hi, 8
	s_add_u32 vcc_lo, vcc_lo, vcc_hi
	s_add_u32 vcc_lo, vcc_lo, 0x5888000
	s_add_u32 s38, s38, vcc_lo
	s_addc_u32 s39, s39, 0
	v_and_b32_e32 v244, 0x3ff, v0
	v_min_u32_e32 v244, 0x191, v244
	v_mul_u32_u24_e32 v245, 0x2aab, v244
	v_lshrrev_b32_e32 v245, 16, v245
	v_mul_u32_u24_e32 v246, 6, v245
	v_sub_u32_e32 v246, v244, v246
	v_mul_u32_u24_e32 v245, 0x1800, v245
	v_lshrrev_b32_e32 v247, 1, v246
	v_lshlrev_b32_e32 v247, 11, v247
	v_and_b32_e32 v246, 1, v246
	v_lshlrev_b32_e32 v246, 7, v246
	v_add3_u32 v244, v245, v247, v246
	v_mov_b32_e32 v245, 0
	v_lshl_add_u64 v[244:245], s[38:39], 0, v[244:245]
	s_mov_b32 m0, 0x26000
	s_nop 0
	global_load_lds_dword v[244:245], off
	ds_read_b128 v[10:13], v229
	ds_read_b128 v[6:9], v229 offset:64
	ds_read_b128 v[2:5], v229 offset:128
	s_mov_b64 s[38:39], -1
	s_and_b64 vcc, exec, s[8:9]
	s_cbranch_vccz .LBB0_184
	ds_read_b128 v[14:17], v208 offset:17408
	ds_read_b128 v[22:25], v229 offset:4352
	ds_read_b128 v[26:29], v229 offset:8704
	ds_read_b128 v[30:33], v229 offset:13056
	s_waitcnt lgkmcnt(3)
	v_mfma_f32_16x16x32_bf16 v[18:21], v[10:13], v[14:17], 0
	ds_read_b128 v[34:37], v229 offset:4416
	s_waitcnt lgkmcnt(3)
	v_mfma_f32_16x16x32_bf16 v[22:25], v[22:25], v[14:17], 0
	s_waitcnt lgkmcnt(2)
	v_mfma_f32_16x16x32_bf16 v[26:29], v[26:29], v[14:17], 0
	s_waitcnt lgkmcnt(1)
	v_mfma_f32_16x16x32_bf16 v[14:17], v[30:33], v[14:17], 0
	ds_read_b128 v[30:33], v208 offset:17472
	s_waitcnt lgkmcnt(0)
	v_mfma_f32_16x16x32_bf16 v[22:25], v[34:37], v[30:33], v[22:25]
	ds_read_b128 v[34:37], v229 offset:8768
	s_waitcnt lgkmcnt(0)
	v_mfma_f32_16x16x32_bf16 v[26:29], v[34:37], v[30:33], v[26:29]
	ds_read_b128 v[34:37], v229 offset:13120
	v_mfma_f32_16x16x32_bf16 v[18:21], v[6:9], v[30:33], v[18:21]
	s_waitcnt lgkmcnt(0)
	v_mfma_f32_16x16x32_bf16 v[14:17], v[34:37], v[30:33], v[14:17]
	ds_read_b128 v[30:33], v208 offset:17536
	ds_read_b128 v[34:37], v229 offset:4480
	s_waitcnt lgkmcnt(0)
	v_mfma_f32_16x16x32_bf16 v[22:25], v[34:37], v[30:33], v[22:25]
	ds_read_b128 v[34:37], v229 offset:8832
	s_waitcnt lgkmcnt(0)
	v_mfma_f32_16x16x32_bf16 v[34:37], v[34:37], v[30:33], v[26:29]
	s_nop 2
	ds_read_b128 v[26:29], v229 offset:13184
	v_mfma_f32_16x16x32_bf16 v[18:21], v[2:5], v[30:33], v[18:21]
	s_waitcnt lgkmcnt(0)
	v_mfma_f32_16x16x32_bf16 v[14:17], v[26:29], v[30:33], v[14:17]
	ds_read_b128 v[30:33], v208 offset:17600
	ds_read_b128 v[26:29], v229 offset:192
	s_waitcnt lgkmcnt(0)
	v_mfma_f32_16x16x32_bf16 v[26:29], v[26:29], v[30:33], v[18:21]
	s_nop 2
	ds_read_b128 v[18:21], v229 offset:4544
	s_waitcnt lgkmcnt(0)
	v_mfma_f32_16x16x32_bf16 v[22:25], v[18:21], v[30:33], v[22:25]
	ds_read_b128 v[18:21], v229 offset:8896
	s_waitcnt lgkmcnt(0)
	v_mfma_f32_16x16x32_bf16 v[18:21], v[18:21], v[30:33], v[34:37]
	s_nop 2
	ds_read_b128 v[34:37], v229 offset:13248
	s_waitcnt lgkmcnt(0)
	v_mfma_f32_16x16x32_bf16 v[14:17], v[34:37], v[30:33], v[14:17]
	ds_read_b32 v30, v184
	v_mov_b32_e32 v31, 0
	v_mov_b32_e32 v32, 0
	s_mov_b64 s[38:39], exec
	v_readlane_b32 s40, v251, 57
	v_readlane_b32 s41, v251, 58
	s_and_b64 s[40:41], s[38:39], s[40:41]
	s_mov_b64 exec, s[40:41]
	s_cbranch_execz .LBB0_155
	ds_read_b32 v32, v144
	s_waitcnt lgkmcnt(0)
	v_sub_f32_e32 v32, v30, v32
	v_mul_f32_e32 v32, 0x3fb8aa3b, v32
	v_exp_f32_e32 v32, v32
	s_nop 0
	v_mul_f32_e32 v32, v26, v32
